# GEMM K-loops: on top of the chained A-row-major MFMA order, the s_setprio 0/1 toggle in the middle of each 32-MFMA block removed (one raise per block)
# speedup vs baseline: 1.0035x; 1.0035x over previous
.LBB0_260:
	v_add_u32_e32 v168, 0x10000, v232
	v_add_u32_e32 v180, 0x14000, v232
	v_lshl_add_u64 v[224:225], v[222:223], 0, s[62:63]
	s_add_i32 m0, s35, 0xc000
	s_waitcnt lgkmcnt(0)
	ds_read_b128 v[148:151], v207
	ds_read_b128 v[164:167], v207 offset:1024
	ds_read_b128 v[144:147], v207 offset:2048
	ds_read_b128 v[160:163], v207 offset:3072
	ds_read_b128 v[140:143], v207 offset:4096
	ds_read_b128 v[156:159], v207 offset:5120
	ds_read_b128 v[136:139], v207 offset:6144
	ds_read_b128 v[152:155], v207 offset:7168
	ds_read_b128 v[184:187], v168
	ds_read_b128 v[188:191], v168 offset:1024
	ds_read_b128 v[192:195], v168 offset:2048
	ds_read_b128 v[196:199], v168 offset:3072
	ds_read_b128 v[168:171], v180
	ds_read_b128 v[172:175], v180 offset:1024
	ds_read_b128 v[176:179], v180 offset:2048
	ds_read_b128 v[180:183], v180 offset:3072
	global_load_lds_dwordx4 v[224:225], off
	v_lshl_add_u64 v[224:225], v[220:221], 0, s[62:63]
	s_add_i32 m0, s35, 0xe000
	s_nop 0
	global_load_lds_dwordx4 v[224:225], off
	s_waitcnt vmcnt(8)
	s_waitcnt lgkmcnt(0)
	s_barrier
	s_setprio 1
	s_waitcnt lgkmcnt(0)
	v_mfma_f32_16x16x32_bf16 v[132:135], v[184:187], v[148:151], v[132:135]
	v_mfma_f32_16x16x32_bf16 v[132:135], v[188:191], v[164:167], v[132:135]
	v_mfma_f32_16x16x32_bf16 v[128:131], v[192:195], v[148:151], v[128:131]
	v_mfma_f32_16x16x32_bf16 v[128:131], v[196:199], v[164:167], v[128:131]
	v_mfma_f32_16x16x32_bf16 v[124:127], v[168:171], v[148:151], v[124:127]
	v_mfma_f32_16x16x32_bf16 v[124:127], v[172:175], v[164:167], v[124:127]
	v_mfma_f32_16x16x32_bf16 v[120:123], v[176:179], v[148:151], v[120:123]
	v_mfma_f32_16x16x32_bf16 v[120:123], v[180:183], v[164:167], v[120:123]
	v_mfma_f32_16x16x32_bf16 v[116:119], v[184:187], v[144:147], v[116:119]
	v_mfma_f32_16x16x32_bf16 v[116:119], v[188:191], v[160:163], v[116:119]
	v_mfma_f32_16x16x32_bf16 v[112:115], v[192:195], v[144:147], v[112:115]
	v_mfma_f32_16x16x32_bf16 v[112:115], v[196:199], v[160:163], v[112:115]
	v_mfma_f32_16x16x32_bf16 v[108:111], v[168:171], v[144:147], v[108:111]
	v_mfma_f32_16x16x32_bf16 v[108:111], v[172:175], v[160:163], v[108:111]
	v_mfma_f32_16x16x32_bf16 v[104:107], v[176:179], v[144:147], v[104:107]
	v_mfma_f32_16x16x32_bf16 v[104:107], v[180:183], v[160:163], v[104:107]
	v_mfma_f32_16x16x32_bf16 v[100:103], v[184:187], v[140:143], v[100:103]
	v_mfma_f32_16x16x32_bf16 v[100:103], v[188:191], v[156:159], v[100:103]
	v_mfma_f32_16x16x32_bf16 v[96:99], v[192:195], v[140:143], v[96:99]
	v_mfma_f32_16x16x32_bf16 v[96:99], v[196:199], v[156:159], v[96:99]
	v_mfma_f32_16x16x32_bf16 v[92:95], v[168:171], v[140:143], v[92:95]
	v_mfma_f32_16x16x32_bf16 v[92:95], v[172:175], v[156:159], v[92:95]
	v_mfma_f32_16x16x32_bf16 v[88:91], v[176:179], v[140:143], v[88:91]
	v_mfma_f32_16x16x32_bf16 v[88:91], v[180:183], v[156:159], v[88:91]
	v_mfma_f32_16x16x32_bf16 v[84:87], v[184:187], v[136:139], v[84:87]
	v_mfma_f32_16x16x32_bf16 v[84:87], v[188:191], v[152:155], v[84:87]
	v_mfma_f32_16x16x32_bf16 v[80:83], v[192:195], v[136:139], v[80:83]
	v_mfma_f32_16x16x32_bf16 v[80:83], v[196:199], v[152:155], v[80:83]
	v_mfma_f32_16x16x32_bf16 v[76:79], v[168:171], v[136:139], v[76:79]
	v_mfma_f32_16x16x32_bf16 v[76:79], v[172:175], v[152:155], v[76:79]
	v_mfma_f32_16x16x32_bf16 v[72:75], v[176:179], v[136:139], v[72:75]
	v_mfma_f32_16x16x32_bf16 v[72:75], v[180:183], v[152:155], v[72:75]
	s_setprio 0
	s_barrier
	v_cndmask_b32_e64 v204, 0, 1, s[60:61]
	v_cmp_ne_u32_e64 s[50:51], 1, v204
	s_andn2_b64 vcc, exec, s[60:61]
	s_cbranch_vccnz .LBB0_262
	ds_read_b128 v[148:151], v207 offset:16384
	ds_read_b128 v[164:167], v207 offset:17408
	ds_read_b128 v[144:147], v207 offset:18432
	ds_read_b128 v[160:163], v207 offset:19456
	ds_read_b128 v[140:143], v207 offset:20480
	ds_read_b128 v[156:159], v207 offset:21504
	ds_read_b128 v[136:139], v207 offset:22528
	ds_read_b128 v[152:155], v207 offset:23552
.LBB0_262:
	s_add_u32 s12, s58, s62
	s_addc_u32 s13, s59, s63
	s_add_u32 s14, s12, 0x100
	s_addc_u32 s15, s13, 0
	s_add_u32 s75, s26, s62
	s_addc_u32 s76, s27, s63
	s_cmpk_eq_i32 s62, 0xf00
	s_cselect_b64 s[52:53], -1, 0
	s_and_b64 s[12:13], s[52:53], exec
	s_cselect_b32 s13, s21, s76
	s_cselect_b32 s12, s73, s75
	s_mov_b32 m0, s38
	s_cselect_b32 s15, s25, s15
	s_cselect_b32 s14, s33, s14
	v_lshl_add_u64 v[224:225], s[12:13], 0, v[208:209]
	s_add_u32 s76, s12, 0x80000
	global_load_lds_dwordx4 v[224:225], off
	v_lshl_add_u64 v[226:227], s[12:13], 0, v[212:213]
	s_mov_b32 m0, s39
	s_addc_u32 s77, s13, 0
	global_load_lds_dwordx4 v[226:227], off
	v_lshl_add_u64 v[228:229], s[76:77], 0, v[208:209]
	s_mov_b32 m0, s40
	v_lshl_add_u64 v[230:231], s[14:15], 0, v[210:211]
	global_load_lds_dwordx4 v[228:229], off
	v_lshl_add_u64 v[228:229], s[76:77], 0, v[212:213]
	s_mov_b32 m0, s41
	s_and_b64 vcc, exec, s[50:51]
	global_load_lds_dwordx4 v[228:229], off
	v_lshl_add_u64 v[228:229], s[14:15], 0, v[4:5]
	s_mov_b32 m0, s35
	s_nop 0
	global_load_lds_dwordx4 v[228:229], off
	s_mov_b32 m0, s43
	s_nop 0
	global_load_lds_dwordx4 v[230:231], off
	s_waitcnt vmcnt(8)
	s_waitcnt lgkmcnt(0)
	s_barrier
	s_cbranch_vccnz .LBB0_264
	s_setprio 1
	s_waitcnt lgkmcnt(0)
	v_mfma_f32_16x16x32_bf16 v[68:71], v[184:187], v[148:151], v[68:71]
	v_mfma_f32_16x16x32_bf16 v[68:71], v[188:191], v[164:167], v[68:71]
	v_mfma_f32_16x16x32_bf16 v[64:67], v[192:195], v[148:151], v[64:67]
	v_mfma_f32_16x16x32_bf16 v[64:67], v[196:199], v[164:167], v[64:67]
	v_mfma_f32_16x16x32_bf16 v[60:63], v[168:171], v[148:151], v[60:63]
	v_mfma_f32_16x16x32_bf16 v[60:63], v[172:175], v[164:167], v[60:63]
	v_mfma_f32_16x16x32_bf16 v[56:59], v[176:179], v[148:151], v[56:59]
	v_mfma_f32_16x16x32_bf16 v[56:59], v[180:183], v[164:167], v[56:59]
	v_mfma_f32_16x16x32_bf16 v[52:55], v[184:187], v[144:147], v[52:55]
	v_mfma_f32_16x16x32_bf16 v[52:55], v[188:191], v[160:163], v[52:55]
	v_mfma_f32_16x16x32_bf16 v[48:51], v[192:195], v[144:147], v[48:51]
	v_mfma_f32_16x16x32_bf16 v[48:51], v[196:199], v[160:163], v[48:51]
	v_mfma_f32_16x16x32_bf16 v[44:47], v[168:171], v[144:147], v[44:47]
	v_mfma_f32_16x16x32_bf16 v[44:47], v[172:175], v[160:163], v[44:47]
	v_mfma_f32_16x16x32_bf16 v[40:43], v[176:179], v[144:147], v[40:43]
	v_mfma_f32_16x16x32_bf16 v[40:43], v[180:183], v[160:163], v[40:43]
	v_mfma_f32_16x16x32_bf16 v[36:39], v[184:187], v[140:143], v[36:39]
	v_mfma_f32_16x16x32_bf16 v[36:39], v[188:191], v[156:159], v[36:39]
	v_mfma_f32_16x16x32_bf16 v[32:35], v[192:195], v[140:143], v[32:35]
	v_mfma_f32_16x16x32_bf16 v[32:35], v[196:199], v[156:159], v[32:35]
	v_mfma_f32_16x16x32_bf16 v[28:31], v[168:171], v[140:143], v[28:31]
	v_mfma_f32_16x16x32_bf16 v[28:31], v[172:175], v[156:159], v[28:31]
	v_mfma_f32_16x16x32_bf16 v[24:27], v[176:179], v[140:143], v[24:27]
	v_mfma_f32_16x16x32_bf16 v[24:27], v[180:183], v[156:159], v[24:27]
	v_mfma_f32_16x16x32_bf16 v[20:23], v[184:187], v[136:139], v[20:23]
	v_mfma_f32_16x16x32_bf16 v[20:23], v[188:191], v[152:155], v[20:23]
	v_mfma_f32_16x16x32_bf16 v[16:19], v[192:195], v[136:139], v[16:19]
	v_mfma_f32_16x16x32_bf16 v[16:19], v[196:199], v[152:155], v[16:19]
	v_mfma_f32_16x16x32_bf16 v[12:15], v[168:171], v[136:139], v[12:15]
	v_mfma_f32_16x16x32_bf16 v[12:15], v[172:175], v[152:155], v[12:15]
	v_mfma_f32_16x16x32_bf16 v[8:11], v[176:179], v[136:139], v[8:11]
	v_mfma_f32_16x16x32_bf16 v[8:11], v[180:183], v[152:155], v[8:11]
	s_setprio 0
.LBB0_264:
	s_barrier
	v_cndmask_b32_e64 v241, v219, 0, s[52:53]
	v_cndmask_b32_e64 v240, v218, v2, s[52:53]
	v_lshl_add_u64 v[240:241], s[14:15], 0, v[240:241]
	s_mov_b32 m0, s45
	v_add_u32_e32 v168, 0x18000, v232
	v_add_u32_e32 v180, 0x1c000, v232
	v_lshl_add_u64 v[242:243], v[240:241], 0, v[4:5]
	s_waitcnt lgkmcnt(0)
	ds_read_b128 v[148:151], v207 offset:32768
	ds_read_b128 v[164:167], v207 offset:33792
	ds_read_b128 v[144:147], v207 offset:34816
	ds_read_b128 v[160:163], v207 offset:35840
	ds_read_b128 v[140:143], v207 offset:36864
	ds_read_b128 v[156:159], v207 offset:37888
	ds_read_b128 v[136:139], v207 offset:38912
	ds_read_b128 v[152:155], v207 offset:39936
	ds_read_b128 v[184:187], v168
	ds_read_b128 v[188:191], v168 offset:1024
	ds_read_b128 v[192:195], v168 offset:2048
	ds_read_b128 v[196:199], v168 offset:3072
	ds_read_b128 v[168:171], v180
	ds_read_b128 v[172:175], v180 offset:1024
	ds_read_b128 v[176:179], v180 offset:2048
	ds_read_b128 v[180:183], v180 offset:3072
	global_load_lds_dwordx4 v[242:243], off
	v_lshl_add_u64 v[240:241], v[240:241], 0, v[210:211]
	s_mov_b32 m0, s47
	s_nop 0
	global_load_lds_dwordx4 v[240:241], off
	s_waitcnt vmcnt(8)
	s_waitcnt lgkmcnt(0)
	s_barrier
	s_setprio 1
	s_waitcnt lgkmcnt(0)
	v_mfma_f32_16x16x32_bf16 v[132:135], v[184:187], v[148:151], v[132:135]
	v_mfma_f32_16x16x32_bf16 v[132:135], v[188:191], v[164:167], v[132:135]
	v_mfma_f32_16x16x32_bf16 v[128:131], v[192:195], v[148:151], v[128:131]
	v_mfma_f32_16x16x32_bf16 v[128:131], v[196:199], v[164:167], v[128:131]
	v_mfma_f32_16x16x32_bf16 v[124:127], v[168:171], v[148:151], v[124:127]
	v_mfma_f32_16x16x32_bf16 v[124:127], v[172:175], v[164:167], v[124:127]
	v_mfma_f32_16x16x32_bf16 v[120:123], v[176:179], v[148:151], v[120:123]
	v_mfma_f32_16x16x32_bf16 v[120:123], v[180:183], v[164:167], v[120:123]
	v_mfma_f32_16x16x32_bf16 v[116:119], v[184:187], v[144:147], v[116:119]
	v_mfma_f32_16x16x32_bf16 v[116:119], v[188:191], v[160:163], v[116:119]
	v_mfma_f32_16x16x32_bf16 v[112:115], v[192:195], v[144:147], v[112:115]
	v_mfma_f32_16x16x32_bf16 v[112:115], v[196:199], v[160:163], v[112:115]
	v_mfma_f32_16x16x32_bf16 v[108:111], v[168:171], v[144:147], v[108:111]
	v_mfma_f32_16x16x32_bf16 v[108:111], v[172:175], v[160:163], v[108:111]
	v_mfma_f32_16x16x32_bf16 v[104:107], v[176:179], v[144:147], v[104:107]
	v_mfma_f32_16x16x32_bf16 v[104:107], v[180:183], v[160:163], v[104:107]
	v_mfma_f32_16x16x32_bf16 v[100:103], v[184:187], v[140:143], v[100:103]
	v_mfma_f32_16x16x32_bf16 v[100:103], v[188:191], v[156:159], v[100:103]
	v_mfma_f32_16x16x32_bf16 v[96:99], v[192:195], v[140:143], v[96:99]
	v_mfma_f32_16x16x32_bf16 v[96:99], v[196:199], v[156:159], v[96:99]
	v_mfma_f32_16x16x32_bf16 v[92:95], v[168:171], v[140:143], v[92:95]
	v_mfma_f32_16x16x32_bf16 v[92:95], v[172:175], v[156:159], v[92:95]
	v_mfma_f32_16x16x32_bf16 v[88:91], v[176:179], v[140:143], v[88:91]
	v_mfma_f32_16x16x32_bf16 v[88:91], v[180:183], v[156:159], v[88:91]
	v_mfma_f32_16x16x32_bf16 v[84:87], v[184:187], v[136:139], v[84:87]
	v_mfma_f32_16x16x32_bf16 v[84:87], v[188:191], v[152:155], v[84:87]
	v_mfma_f32_16x16x32_bf16 v[80:83], v[192:195], v[136:139], v[80:83]
	v_mfma_f32_16x16x32_bf16 v[80:83], v[196:199], v[152:155], v[80:83]
	v_mfma_f32_16x16x32_bf16 v[76:79], v[168:171], v[136:139], v[76:79]
	v_mfma_f32_16x16x32_bf16 v[76:79], v[172:175], v[152:155], v[76:79]
	v_mfma_f32_16x16x32_bf16 v[72:75], v[176:179], v[136:139], v[72:75]
	v_mfma_f32_16x16x32_bf16 v[72:75], v[180:183], v[152:155], v[72:75]
	s_setprio 0
	s_barrier
	s_and_b64 vcc, exec, s[50:51]
	s_cbranch_vccnz .LBB0_266
	ds_read_b128 v[148:151], v207 offset:49152
	ds_read_b128 v[164:167], v207 offset:50176
	ds_read_b128 v[144:147], v207 offset:51200
	ds_read_b128 v[160:163], v207 offset:52224
	ds_read_b128 v[140:143], v207 offset:53248
	ds_read_b128 v[156:159], v207 offset:54272
	ds_read_b128 v[136:139], v207 offset:55296
	ds_read_b128 v[152:155], v207 offset:56320
.LBB0_266:
	s_mov_b32 m0, s64
	v_lshl_add_u64 v[224:225], v[224:225], 0, s[0:1]
	s_add_u32 s12, s12, 0x80080
	global_load_lds_dwordx4 v[224:225], off
	v_lshl_add_u64 v[224:225], v[226:227], 0, s[0:1]
	s_mov_b32 m0, s65
	s_addc_u32 s13, s13, 0
	global_load_lds_dwordx4 v[224:225], off
	v_lshl_add_u64 v[224:225], s[12:13], 0, v[208:209]
	s_mov_b32 m0, s68
	s_and_b64 vcc, exec, s[50:51]
	global_load_lds_dwordx4 v[224:225], off
	v_lshl_add_u64 v[224:225], s[12:13], 0, v[212:213]
	s_mov_b32 m0, s69
	s_nop 0
	global_load_lds_dwordx4 v[224:225], off
	v_lshl_add_u64 v[224:225], v[228:229], 0, s[0:1]
	s_mov_b32 m0, s66
	s_nop 0
	global_load_lds_dwordx4 v[224:225], off
	v_lshl_add_u64 v[224:225], v[230:231], 0, s[0:1]
	s_mov_b32 m0, s67
	s_nop 0
	global_load_lds_dwordx4 v[224:225], off
	s_waitcnt vmcnt(8)
	s_waitcnt lgkmcnt(0)
	s_barrier
	s_cbranch_vccnz .LBB0_259
	s_setprio 1
	s_waitcnt lgkmcnt(0)
	v_mfma_f32_16x16x32_bf16 v[68:71], v[184:187], v[148:151], v[68:71]
	v_mfma_f32_16x16x32_bf16 v[68:71], v[188:191], v[164:167], v[68:71]
	v_mfma_f32_16x16x32_bf16 v[64:67], v[192:195], v[148:151], v[64:67]
	v_mfma_f32_16x16x32_bf16 v[64:67], v[196:199], v[164:167], v[64:67]
	v_mfma_f32_16x16x32_bf16 v[60:63], v[168:171], v[148:151], v[60:63]
	v_mfma_f32_16x16x32_bf16 v[60:63], v[172:175], v[164:167], v[60:63]
	v_mfma_f32_16x16x32_bf16 v[56:59], v[176:179], v[148:151], v[56:59]
	v_mfma_f32_16x16x32_bf16 v[56:59], v[180:183], v[164:167], v[56:59]
	v_mfma_f32_16x16x32_bf16 v[52:55], v[184:187], v[144:147], v[52:55]
	v_mfma_f32_16x16x32_bf16 v[52:55], v[188:191], v[160:163], v[52:55]
	v_mfma_f32_16x16x32_bf16 v[48:51], v[192:195], v[144:147], v[48:51]
	v_mfma_f32_16x16x32_bf16 v[48:51], v[196:199], v[160:163], v[48:51]
	v_mfma_f32_16x16x32_bf16 v[44:47], v[168:171], v[144:147], v[44:47]
	v_mfma_f32_16x16x32_bf16 v[44:47], v[172:175], v[160:163], v[44:47]
	v_mfma_f32_16x16x32_bf16 v[40:43], v[176:179], v[144:147], v[40:43]
	v_mfma_f32_16x16x32_bf16 v[40:43], v[180:183], v[160:163], v[40:43]
	v_mfma_f32_16x16x32_bf16 v[36:39], v[184:187], v[140:143], v[36:39]
	v_mfma_f32_16x16x32_bf16 v[36:39], v[188:191], v[156:159], v[36:39]
	v_mfma_f32_16x16x32_bf16 v[32:35], v[192:195], v[140:143], v[32:35]
	v_mfma_f32_16x16x32_bf16 v[32:35], v[196:199], v[156:159], v[32:35]
	v_mfma_f32_16x16x32_bf16 v[28:31], v[168:171], v[140:143], v[28:31]
	v_mfma_f32_16x16x32_bf16 v[28:31], v[172:175], v[156:159], v[28:31]
	v_mfma_f32_16x16x32_bf16 v[24:27], v[176:179], v[140:143], v[24:27]
	v_mfma_f32_16x16x32_bf16 v[24:27], v[180:183], v[156:159], v[24:27]
	v_mfma_f32_16x16x32_bf16 v[20:23], v[184:187], v[136:139], v[20:23]
	v_mfma_f32_16x16x32_bf16 v[20:23], v[188:191], v[152:155], v[20:23]
	v_mfma_f32_16x16x32_bf16 v[16:19], v[192:195], v[136:139], v[16:19]
	v_mfma_f32_16x16x32_bf16 v[16:19], v[196:199], v[152:155], v[16:19]
	v_mfma_f32_16x16x32_bf16 v[12:15], v[168:171], v[136:139], v[12:15]
	v_mfma_f32_16x16x32_bf16 v[12:15], v[172:175], v[152:155], v[12:15]
	v_mfma_f32_16x16x32_bf16 v[8:11], v[176:179], v[136:139], v[8:11]
	v_mfma_f32_16x16x32_bf16 v[8:11], v[180:183], v[152:155], v[8:11]
	s_setprio 0
	s_branch .LBB0_259

.LBB0_369:
	v_add_u32_e32 v168, 0x10000, v232
	v_add_u32_e32 v180, 0x14000, v232
	v_lshl_add_u64 v[224:225], v[222:223], 0, s[60:61]
	s_add_i32 m0, s9, 0xc000
	s_waitcnt lgkmcnt(0)
	ds_read_b128 v[148:151], v207
	ds_read_b128 v[164:167], v207 offset:1024
	ds_read_b128 v[144:147], v207 offset:2048
	ds_read_b128 v[160:163], v207 offset:3072
	ds_read_b128 v[140:143], v207 offset:4096
	ds_read_b128 v[156:159], v207 offset:5120
	ds_read_b128 v[136:139], v207 offset:6144
	ds_read_b128 v[152:155], v207 offset:7168
	ds_read_b128 v[184:187], v168
	ds_read_b128 v[188:191], v168 offset:1024
	ds_read_b128 v[192:195], v168 offset:2048
	ds_read_b128 v[196:199], v168 offset:3072
	ds_read_b128 v[168:171], v180
	ds_read_b128 v[172:175], v180 offset:1024
	ds_read_b128 v[176:179], v180 offset:2048
	ds_read_b128 v[180:183], v180 offset:3072
	global_load_lds_dwordx4 v[224:225], off
	v_lshl_add_u64 v[224:225], v[220:221], 0, s[60:61]
	s_add_i32 m0, s9, 0xe000
	s_nop 0
	global_load_lds_dwordx4 v[224:225], off
	s_waitcnt vmcnt(8)
	s_waitcnt lgkmcnt(0)
	s_barrier
	s_setprio 1
	s_waitcnt lgkmcnt(0)
	v_mfma_f32_16x16x32_bf16 v[132:135], v[184:187], v[148:151], v[132:135]
	v_mfma_f32_16x16x32_bf16 v[132:135], v[188:191], v[164:167], v[132:135]
	v_mfma_f32_16x16x32_bf16 v[128:131], v[192:195], v[148:151], v[128:131]
	v_mfma_f32_16x16x32_bf16 v[128:131], v[196:199], v[164:167], v[128:131]
	v_mfma_f32_16x16x32_bf16 v[116:119], v[168:171], v[148:151], v[116:119]
	v_mfma_f32_16x16x32_bf16 v[116:119], v[172:175], v[164:167], v[116:119]
	v_mfma_f32_16x16x32_bf16 v[112:115], v[176:179], v[148:151], v[112:115]
	v_mfma_f32_16x16x32_bf16 v[112:115], v[180:183], v[164:167], v[112:115]
	v_mfma_f32_16x16x32_bf16 v[124:127], v[184:187], v[144:147], v[124:127]
	v_mfma_f32_16x16x32_bf16 v[124:127], v[188:191], v[160:163], v[124:127]
	v_mfma_f32_16x16x32_bf16 v[120:123], v[192:195], v[144:147], v[120:123]
	v_mfma_f32_16x16x32_bf16 v[120:123], v[196:199], v[160:163], v[120:123]
	v_mfma_f32_16x16x32_bf16 v[100:103], v[168:171], v[144:147], v[100:103]
	v_mfma_f32_16x16x32_bf16 v[100:103], v[172:175], v[160:163], v[100:103]
	v_mfma_f32_16x16x32_bf16 v[96:99], v[176:179], v[144:147], v[96:99]
	v_mfma_f32_16x16x32_bf16 v[96:99], v[180:183], v[160:163], v[96:99]
	v_mfma_f32_16x16x32_bf16 v[108:111], v[184:187], v[140:143], v[108:111]
	v_mfma_f32_16x16x32_bf16 v[108:111], v[188:191], v[156:159], v[108:111]
	v_mfma_f32_16x16x32_bf16 v[104:107], v[192:195], v[140:143], v[104:107]
	v_mfma_f32_16x16x32_bf16 v[104:107], v[196:199], v[156:159], v[104:107]
	v_mfma_f32_16x16x32_bf16 v[84:87], v[168:171], v[140:143], v[84:87]
	v_mfma_f32_16x16x32_bf16 v[84:87], v[172:175], v[156:159], v[84:87]
	v_mfma_f32_16x16x32_bf16 v[80:83], v[176:179], v[140:143], v[80:83]
	v_mfma_f32_16x16x32_bf16 v[80:83], v[180:183], v[156:159], v[80:83]
	v_mfma_f32_16x16x32_bf16 v[92:95], v[184:187], v[136:139], v[92:95]
	v_mfma_f32_16x16x32_bf16 v[92:95], v[188:191], v[152:155], v[92:95]
	v_mfma_f32_16x16x32_bf16 v[88:91], v[192:195], v[136:139], v[88:91]
	v_mfma_f32_16x16x32_bf16 v[88:91], v[196:199], v[152:155], v[88:91]
	v_mfma_f32_16x16x32_bf16 v[76:79], v[168:171], v[136:139], v[76:79]
	v_mfma_f32_16x16x32_bf16 v[76:79], v[172:175], v[152:155], v[76:79]
	v_mfma_f32_16x16x32_bf16 v[72:75], v[176:179], v[136:139], v[72:75]
	v_mfma_f32_16x16x32_bf16 v[72:75], v[180:183], v[152:155], v[72:75]
	s_setprio 0
	s_barrier
	v_cndmask_b32_e64 v204, 0, 1, s[58:59]
	v_cmp_ne_u32_e64 s[50:51], 1, v204
	s_andn2_b64 vcc, exec, s[58:59]
	s_cbranch_vccnz .LBB0_371
	ds_read_b128 v[148:151], v207 offset:16384
	ds_read_b128 v[164:167], v207 offset:17408
	ds_read_b128 v[144:147], v207 offset:18432
	ds_read_b128 v[160:163], v207 offset:19456
	ds_read_b128 v[140:143], v207 offset:20480
	ds_read_b128 v[156:159], v207 offset:21504
	ds_read_b128 v[136:139], v207 offset:22528
	ds_read_b128 v[152:155], v207 offset:23552
.LBB0_371:
	s_add_u32 s12, s24, s60
	s_addc_u32 s13, s25, s61
	s_add_u32 s14, s12, 0x100
	s_addc_u32 s15, s13, 0
	s_add_u32 s73, s26, s60
	s_addc_u32 s74, s27, s61
	s_cmpk_eq_i32 s60, 0xf00
	s_cselect_b64 s[52:53], -1, 0
	s_and_b64 s[12:13], s[52:53], exec
	s_cselect_b32 s13, s37, s74
	s_cselect_b32 s12, s43, s73
	s_mov_b32 m0, s38
	s_cselect_b32 s15, s7, s15
	s_cselect_b32 s14, s33, s14
	v_lshl_add_u64 v[224:225], s[12:13], 0, v[208:209]
	s_add_u32 s74, s12, 0x80000
	global_load_lds_dwordx4 v[224:225], off
	v_lshl_add_u64 v[226:227], s[12:13], 0, v[212:213]
	s_mov_b32 m0, s39
	s_addc_u32 s75, s13, 0
	global_load_lds_dwordx4 v[226:227], off
	v_lshl_add_u64 v[228:229], s[74:75], 0, v[208:209]
	s_mov_b32 m0, s40
	v_lshl_add_u64 v[230:231], s[14:15], 0, v[210:211]
	global_load_lds_dwordx4 v[228:229], off
	v_lshl_add_u64 v[228:229], s[74:75], 0, v[212:213]
	s_mov_b32 m0, s41
	s_and_b64 vcc, exec, s[50:51]
	global_load_lds_dwordx4 v[228:229], off
	v_lshl_add_u64 v[228:229], s[14:15], 0, v[4:5]
	s_mov_b32 m0, s9
	s_nop 0
	global_load_lds_dwordx4 v[228:229], off
	s_mov_b32 m0, s47
	s_nop 0
	global_load_lds_dwordx4 v[230:231], off
	s_waitcnt vmcnt(8)
	s_waitcnt lgkmcnt(0)
	s_barrier
	s_cbranch_vccnz .LBB0_373
	s_setprio 1
	s_waitcnt lgkmcnt(0)
	v_mfma_f32_16x16x32_bf16 v[68:71], v[184:187], v[148:151], v[68:71]
	v_mfma_f32_16x16x32_bf16 v[68:71], v[188:191], v[164:167], v[68:71]
	v_mfma_f32_16x16x32_bf16 v[64:67], v[192:195], v[148:151], v[64:67]
	v_mfma_f32_16x16x32_bf16 v[64:67], v[196:199], v[164:167], v[64:67]
	v_mfma_f32_16x16x32_bf16 v[60:63], v[168:171], v[148:151], v[60:63]
	v_mfma_f32_16x16x32_bf16 v[60:63], v[172:175], v[164:167], v[60:63]
	v_mfma_f32_16x16x32_bf16 v[56:59], v[176:179], v[148:151], v[56:59]
	v_mfma_f32_16x16x32_bf16 v[56:59], v[180:183], v[164:167], v[56:59]
	v_mfma_f32_16x16x32_bf16 v[52:55], v[184:187], v[144:147], v[52:55]
	v_mfma_f32_16x16x32_bf16 v[52:55], v[188:191], v[160:163], v[52:55]
	v_mfma_f32_16x16x32_bf16 v[48:51], v[192:195], v[144:147], v[48:51]
	v_mfma_f32_16x16x32_bf16 v[48:51], v[196:199], v[160:163], v[48:51]
	v_mfma_f32_16x16x32_bf16 v[44:47], v[168:171], v[144:147], v[44:47]
	v_mfma_f32_16x16x32_bf16 v[44:47], v[172:175], v[160:163], v[44:47]
	v_mfma_f32_16x16x32_bf16 v[40:43], v[176:179], v[144:147], v[40:43]
	v_mfma_f32_16x16x32_bf16 v[40:43], v[180:183], v[160:163], v[40:43]
	v_mfma_f32_16x16x32_bf16 v[36:39], v[184:187], v[140:143], v[36:39]
	v_mfma_f32_16x16x32_bf16 v[36:39], v[188:191], v[156:159], v[36:39]
	v_mfma_f32_16x16x32_bf16 v[32:35], v[192:195], v[140:143], v[32:35]
	v_mfma_f32_16x16x32_bf16 v[32:35], v[196:199], v[156:159], v[32:35]
	v_mfma_f32_16x16x32_bf16 v[28:31], v[168:171], v[140:143], v[28:31]
	v_mfma_f32_16x16x32_bf16 v[28:31], v[172:175], v[156:159], v[28:31]
	v_mfma_f32_16x16x32_bf16 v[24:27], v[176:179], v[140:143], v[24:27]
	v_mfma_f32_16x16x32_bf16 v[24:27], v[180:183], v[156:159], v[24:27]
	v_mfma_f32_16x16x32_bf16 v[20:23], v[184:187], v[136:139], v[20:23]
	v_mfma_f32_16x16x32_bf16 v[20:23], v[188:191], v[152:155], v[20:23]
	v_mfma_f32_16x16x32_bf16 v[16:19], v[192:195], v[136:139], v[16:19]
	v_mfma_f32_16x16x32_bf16 v[16:19], v[196:199], v[152:155], v[16:19]
	v_mfma_f32_16x16x32_bf16 v[12:15], v[168:171], v[136:139], v[12:15]
	v_mfma_f32_16x16x32_bf16 v[12:15], v[172:175], v[152:155], v[12:15]
	v_mfma_f32_16x16x32_bf16 v[8:11], v[176:179], v[136:139], v[8:11]
	v_mfma_f32_16x16x32_bf16 v[8:11], v[180:183], v[152:155], v[8:11]
	s_setprio 0
.LBB0_373:
	s_barrier
	v_cndmask_b32_e64 v241, v219, 0, s[52:53]
	v_cndmask_b32_e64 v240, v218, v2, s[52:53]
	v_lshl_add_u64 v[240:241], s[14:15], 0, v[240:241]
	s_mov_b32 m0, s62
	v_add_u32_e32 v168, 0x18000, v232
	v_add_u32_e32 v180, 0x1c000, v232
	v_lshl_add_u64 v[242:243], v[240:241], 0, v[4:5]
	s_waitcnt lgkmcnt(0)
	ds_read_b128 v[148:151], v207 offset:32768
	ds_read_b128 v[164:167], v207 offset:33792
	ds_read_b128 v[144:147], v207 offset:34816
	ds_read_b128 v[160:163], v207 offset:35840
	ds_read_b128 v[140:143], v207 offset:36864
	ds_read_b128 v[156:159], v207 offset:37888
	ds_read_b128 v[136:139], v207 offset:38912
	ds_read_b128 v[152:155], v207 offset:39936
	ds_read_b128 v[184:187], v168
	ds_read_b128 v[188:191], v168 offset:1024
	ds_read_b128 v[192:195], v168 offset:2048
	ds_read_b128 v[196:199], v168 offset:3072
	ds_read_b128 v[168:171], v180
	ds_read_b128 v[172:175], v180 offset:1024
	ds_read_b128 v[176:179], v180 offset:2048
	ds_read_b128 v[180:183], v180 offset:3072
	global_load_lds_dwordx4 v[242:243], off
	v_lshl_add_u64 v[240:241], v[240:241], 0, v[210:211]
	s_mov_b32 m0, s63
	s_nop 0
	global_load_lds_dwordx4 v[240:241], off
	s_waitcnt vmcnt(8)
	s_waitcnt lgkmcnt(0)
	s_barrier
	s_setprio 1
	s_waitcnt lgkmcnt(0)
	v_mfma_f32_16x16x32_bf16 v[132:135], v[184:187], v[148:151], v[132:135]
	v_mfma_f32_16x16x32_bf16 v[132:135], v[188:191], v[164:167], v[132:135]
	v_mfma_f32_16x16x32_bf16 v[128:131], v[192:195], v[148:151], v[128:131]
	v_mfma_f32_16x16x32_bf16 v[128:131], v[196:199], v[164:167], v[128:131]
	v_mfma_f32_16x16x32_bf16 v[116:119], v[168:171], v[148:151], v[116:119]
	v_mfma_f32_16x16x32_bf16 v[116:119], v[172:175], v[164:167], v[116:119]
	v_mfma_f32_16x16x32_bf16 v[112:115], v[176:179], v[148:151], v[112:115]
	v_mfma_f32_16x16x32_bf16 v[112:115], v[180:183], v[164:167], v[112:115]
	v_mfma_f32_16x16x32_bf16 v[124:127], v[184:187], v[144:147], v[124:127]
	v_mfma_f32_16x16x32_bf16 v[124:127], v[188:191], v[160:163], v[124:127]
	v_mfma_f32_16x16x32_bf16 v[120:123], v[192:195], v[144:147], v[120:123]
	v_mfma_f32_16x16x32_bf16 v[120:123], v[196:199], v[160:163], v[120:123]
	v_mfma_f32_16x16x32_bf16 v[100:103], v[168:171], v[144:147], v[100:103]
	v_mfma_f32_16x16x32_bf16 v[100:103], v[172:175], v[160:163], v[100:103]
	v_mfma_f32_16x16x32_bf16 v[96:99], v[176:179], v[144:147], v[96:99]
	v_mfma_f32_16x16x32_bf16 v[96:99], v[180:183], v[160:163], v[96:99]
	v_mfma_f32_16x16x32_bf16 v[108:111], v[184:187], v[140:143], v[108:111]
	v_mfma_f32_16x16x32_bf16 v[108:111], v[188:191], v[156:159], v[108:111]
	v_mfma_f32_16x16x32_bf16 v[104:107], v[192:195], v[140:143], v[104:107]
	v_mfma_f32_16x16x32_bf16 v[104:107], v[196:199], v[156:159], v[104:107]
	v_mfma_f32_16x16x32_bf16 v[84:87], v[168:171], v[140:143], v[84:87]
	v_mfma_f32_16x16x32_bf16 v[84:87], v[172:175], v[156:159], v[84:87]
	v_mfma_f32_16x16x32_bf16 v[80:83], v[176:179], v[140:143], v[80:83]
	v_mfma_f32_16x16x32_bf16 v[80:83], v[180:183], v[156:159], v[80:83]
	v_mfma_f32_16x16x32_bf16 v[92:95], v[184:187], v[136:139], v[92:95]
	v_mfma_f32_16x16x32_bf16 v[92:95], v[188:191], v[152:155], v[92:95]
	v_mfma_f32_16x16x32_bf16 v[88:91], v[192:195], v[136:139], v[88:91]
	v_mfma_f32_16x16x32_bf16 v[88:91], v[196:199], v[152:155], v[88:91]
	v_mfma_f32_16x16x32_bf16 v[76:79], v[168:171], v[136:139], v[76:79]
	v_mfma_f32_16x16x32_bf16 v[76:79], v[172:175], v[152:155], v[76:79]
	v_mfma_f32_16x16x32_bf16 v[72:75], v[176:179], v[136:139], v[72:75]
	v_mfma_f32_16x16x32_bf16 v[72:75], v[180:183], v[152:155], v[72:75]
	s_setprio 0
	s_barrier
	s_and_b64 vcc, exec, s[50:51]
	s_cbranch_vccnz .LBB0_375
	ds_read_b128 v[148:151], v207 offset:49152
	ds_read_b128 v[164:167], v207 offset:50176
	ds_read_b128 v[144:147], v207 offset:51200
	ds_read_b128 v[160:163], v207 offset:52224
	ds_read_b128 v[140:143], v207 offset:53248
	ds_read_b128 v[156:159], v207 offset:54272
	ds_read_b128 v[136:139], v207 offset:55296
	ds_read_b128 v[152:155], v207 offset:56320

.LBB0_559:
	v_add_u32_e32 v168, 0x10000, v240
	v_add_u32_e32 v180, 0x14000, v240
	v_lshl_add_u64 v[226:227], v[224:225], 0, s[64:65]
	s_add_i32 m0, s38, 0xc000
	s_waitcnt lgkmcnt(0)
	ds_read_b128 v[148:151], v239
	ds_read_b128 v[164:167], v239 offset:1024
	ds_read_b128 v[144:147], v239 offset:2048
	ds_read_b128 v[160:163], v239 offset:3072
	ds_read_b128 v[140:143], v239 offset:4096
	ds_read_b128 v[156:159], v239 offset:5120
	ds_read_b128 v[136:139], v239 offset:6144
	ds_read_b128 v[152:155], v239 offset:7168
	ds_read_b128 v[184:187], v168
	ds_read_b128 v[188:191], v168 offset:1024
	ds_read_b128 v[192:195], v168 offset:2048
	ds_read_b128 v[196:199], v168 offset:3072
	ds_read_b128 v[168:171], v180
	ds_read_b128 v[172:175], v180 offset:1024
	ds_read_b128 v[176:179], v180 offset:2048
	ds_read_b128 v[180:183], v180 offset:3072
	global_load_lds_dwordx4 v[226:227], off
	v_lshl_add_u64 v[226:227], v[222:223], 0, s[64:65]
	s_add_i32 m0, s38, 0xe000
	s_nop 0
	global_load_lds_dwordx4 v[226:227], off
	s_waitcnt vmcnt(8)
	s_waitcnt lgkmcnt(0)
	s_barrier
	s_setprio 1
	s_waitcnt lgkmcnt(0)
	v_mfma_f32_16x16x32_bf16 v[132:135], v[184:187], v[148:151], v[132:135]
	v_mfma_f32_16x16x32_bf16 v[132:135], v[188:191], v[164:167], v[132:135]
	v_mfma_f32_16x16x32_bf16 v[128:131], v[192:195], v[148:151], v[128:131]
	v_mfma_f32_16x16x32_bf16 v[128:131], v[196:199], v[164:167], v[128:131]
	v_mfma_f32_16x16x32_bf16 v[124:127], v[168:171], v[148:151], v[124:127]
	v_mfma_f32_16x16x32_bf16 v[124:127], v[172:175], v[164:167], v[124:127]
	v_mfma_f32_16x16x32_bf16 v[120:123], v[176:179], v[148:151], v[120:123]
	v_mfma_f32_16x16x32_bf16 v[120:123], v[180:183], v[164:167], v[120:123]
	v_mfma_f32_16x16x32_bf16 v[116:119], v[184:187], v[144:147], v[116:119]
	v_mfma_f32_16x16x32_bf16 v[116:119], v[188:191], v[160:163], v[116:119]
	v_mfma_f32_16x16x32_bf16 v[112:115], v[192:195], v[144:147], v[112:115]
	v_mfma_f32_16x16x32_bf16 v[112:115], v[196:199], v[160:163], v[112:115]
	v_mfma_f32_16x16x32_bf16 v[108:111], v[168:171], v[144:147], v[108:111]
	v_mfma_f32_16x16x32_bf16 v[108:111], v[172:175], v[160:163], v[108:111]
	v_mfma_f32_16x16x32_bf16 v[104:107], v[176:179], v[144:147], v[104:107]
	v_mfma_f32_16x16x32_bf16 v[104:107], v[180:183], v[160:163], v[104:107]
	v_mfma_f32_16x16x32_bf16 v[100:103], v[184:187], v[140:143], v[100:103]
	v_mfma_f32_16x16x32_bf16 v[100:103], v[188:191], v[156:159], v[100:103]
	v_mfma_f32_16x16x32_bf16 v[96:99], v[192:195], v[140:143], v[96:99]
	v_mfma_f32_16x16x32_bf16 v[96:99], v[196:199], v[156:159], v[96:99]
	v_mfma_f32_16x16x32_bf16 v[92:95], v[168:171], v[140:143], v[92:95]
	v_mfma_f32_16x16x32_bf16 v[92:95], v[172:175], v[156:159], v[92:95]
	v_mfma_f32_16x16x32_bf16 v[88:91], v[176:179], v[140:143], v[88:91]
	v_mfma_f32_16x16x32_bf16 v[88:91], v[180:183], v[156:159], v[88:91]
	v_mfma_f32_16x16x32_bf16 v[84:87], v[184:187], v[136:139], v[84:87]
	v_mfma_f32_16x16x32_bf16 v[84:87], v[188:191], v[152:155], v[84:87]
	v_mfma_f32_16x16x32_bf16 v[80:83], v[192:195], v[136:139], v[80:83]
	v_mfma_f32_16x16x32_bf16 v[80:83], v[196:199], v[152:155], v[80:83]
	v_mfma_f32_16x16x32_bf16 v[76:79], v[168:171], v[136:139], v[76:79]
	v_mfma_f32_16x16x32_bf16 v[76:79], v[172:175], v[152:155], v[76:79]
	v_mfma_f32_16x16x32_bf16 v[72:75], v[176:179], v[136:139], v[72:75]
	v_mfma_f32_16x16x32_bf16 v[72:75], v[180:183], v[152:155], v[72:75]
	s_setprio 0
	s_barrier
	v_cndmask_b32_e64 v204, 0, 1, s[62:63]
	v_cmp_ne_u32_e64 s[50:51], 1, v204
	s_andn2_b64 vcc, exec, s[62:63]
	s_cbranch_vccnz .LBB0_561
	ds_read_b128 v[148:151], v239 offset:16384
	ds_read_b128 v[164:167], v239 offset:17408
	ds_read_b128 v[144:147], v239 offset:18432
	ds_read_b128 v[160:163], v239 offset:19456
	ds_read_b128 v[140:143], v239 offset:20480
	ds_read_b128 v[156:159], v239 offset:21504
	ds_read_b128 v[136:139], v239 offset:22528
	ds_read_b128 v[152:155], v239 offset:23552
.LBB0_561:
	s_add_u32 s12, s60, s64
	s_addc_u32 s13, s61, s65
	s_add_u32 s14, s12, 0x100
	s_addc_u32 s15, s13, 0
	s_add_u32 s79, s26, s64
	s_addc_u32 s80, s27, s65
	s_cmpk_eq_i32 s64, 0x300
	s_cselect_b64 s[52:53], -1, 0
	s_and_b64 s[12:13], s[52:53], exec
	s_cselect_b32 s13, s17, s80
	s_cselect_b32 s12, s35, s79
	s_mov_b32 m0, s39
	s_cselect_b32 s15, s21, s15
	s_cselect_b32 s14, s33, s14
	v_lshl_add_u64 v[226:227], s[12:13], 0, v[4:5]
	s_add_u32 s80, s12, 0x20000
	global_load_lds_dwordx4 v[226:227], off
	v_lshl_add_u64 v[228:229], s[12:13], 0, v[208:209]
	s_mov_b32 m0, s40
	s_addc_u32 s81, s13, 0
	global_load_lds_dwordx4 v[228:229], off
	v_lshl_add_u64 v[230:231], s[80:81], 0, v[4:5]
	s_mov_b32 m0, s41
	v_lshl_add_u64 v[232:233], s[14:15], 0, v[208:209]
	global_load_lds_dwordx4 v[230:231], off
	v_lshl_add_u64 v[230:231], s[80:81], 0, v[208:209]
	s_mov_b32 m0, s47
	s_and_b64 vcc, exec, s[50:51]
	global_load_lds_dwordx4 v[230:231], off
	v_lshl_add_u64 v[230:231], s[14:15], 0, v[4:5]
	s_mov_b32 m0, s38
	s_nop 0
	global_load_lds_dwordx4 v[230:231], off
	s_mov_b32 m0, s59
	s_nop 0
	global_load_lds_dwordx4 v[232:233], off
	s_waitcnt vmcnt(8)
	s_waitcnt lgkmcnt(0)
	s_barrier
	s_cbranch_vccnz .LBB0_563
	s_setprio 1
	s_waitcnt lgkmcnt(0)
	v_mfma_f32_16x16x32_bf16 v[68:71], v[184:187], v[148:151], v[68:71]
	v_mfma_f32_16x16x32_bf16 v[68:71], v[188:191], v[164:167], v[68:71]
	v_mfma_f32_16x16x32_bf16 v[64:67], v[192:195], v[148:151], v[64:67]
	v_mfma_f32_16x16x32_bf16 v[64:67], v[196:199], v[164:167], v[64:67]
	v_mfma_f32_16x16x32_bf16 v[60:63], v[168:171], v[148:151], v[60:63]
	v_mfma_f32_16x16x32_bf16 v[60:63], v[172:175], v[164:167], v[60:63]
	v_mfma_f32_16x16x32_bf16 v[56:59], v[176:179], v[148:151], v[56:59]
	v_mfma_f32_16x16x32_bf16 v[56:59], v[180:183], v[164:167], v[56:59]
	v_mfma_f32_16x16x32_bf16 v[52:55], v[184:187], v[144:147], v[52:55]
	v_mfma_f32_16x16x32_bf16 v[52:55], v[188:191], v[160:163], v[52:55]
	v_mfma_f32_16x16x32_bf16 v[48:51], v[192:195], v[144:147], v[48:51]
	v_mfma_f32_16x16x32_bf16 v[48:51], v[196:199], v[160:163], v[48:51]
	v_mfma_f32_16x16x32_bf16 v[44:47], v[168:171], v[144:147], v[44:47]
	v_mfma_f32_16x16x32_bf16 v[44:47], v[172:175], v[160:163], v[44:47]
	v_mfma_f32_16x16x32_bf16 v[40:43], v[176:179], v[144:147], v[40:43]
	v_mfma_f32_16x16x32_bf16 v[40:43], v[180:183], v[160:163], v[40:43]
	v_mfma_f32_16x16x32_bf16 v[36:39], v[184:187], v[140:143], v[36:39]
	v_mfma_f32_16x16x32_bf16 v[36:39], v[188:191], v[156:159], v[36:39]
	v_mfma_f32_16x16x32_bf16 v[32:35], v[192:195], v[140:143], v[32:35]
	v_mfma_f32_16x16x32_bf16 v[32:35], v[196:199], v[156:159], v[32:35]
	v_mfma_f32_16x16x32_bf16 v[28:31], v[168:171], v[140:143], v[28:31]
	v_mfma_f32_16x16x32_bf16 v[28:31], v[172:175], v[156:159], v[28:31]
	v_mfma_f32_16x16x32_bf16 v[24:27], v[176:179], v[140:143], v[24:27]
	v_mfma_f32_16x16x32_bf16 v[24:27], v[180:183], v[156:159], v[24:27]
	v_mfma_f32_16x16x32_bf16 v[20:23], v[184:187], v[136:139], v[20:23]
	v_mfma_f32_16x16x32_bf16 v[20:23], v[188:191], v[152:155], v[20:23]
	v_mfma_f32_16x16x32_bf16 v[16:19], v[192:195], v[136:139], v[16:19]
	v_mfma_f32_16x16x32_bf16 v[16:19], v[196:199], v[152:155], v[16:19]
	v_mfma_f32_16x16x32_bf16 v[12:15], v[168:171], v[136:139], v[12:15]
	v_mfma_f32_16x16x32_bf16 v[12:15], v[172:175], v[152:155], v[12:15]
	v_mfma_f32_16x16x32_bf16 v[8:11], v[176:179], v[136:139], v[8:11]
	v_mfma_f32_16x16x32_bf16 v[8:11], v[180:183], v[152:155], v[8:11]
	s_setprio 0
.LBB0_563:
	s_barrier
	v_cndmask_b32_e64 v243, v221, 0, s[52:53]
	v_cndmask_b32_e64 v242, v220, v2, s[52:53]
	v_lshl_add_u64 v[242:243], s[14:15], 0, v[242:243]
	s_mov_b32 m0, s66
	v_add_u32_e32 v168, 0x18000, v240
	v_add_u32_e32 v180, 0x1c000, v240
	v_lshl_add_u64 v[204:205], v[242:243], 0, v[4:5]
	s_waitcnt lgkmcnt(0)
	ds_read_b128 v[148:151], v239 offset:32768
	ds_read_b128 v[164:167], v239 offset:33792
	ds_read_b128 v[144:147], v239 offset:34816
	ds_read_b128 v[160:163], v239 offset:35840
	ds_read_b128 v[140:143], v239 offset:36864
	ds_read_b128 v[156:159], v239 offset:37888
	ds_read_b128 v[136:139], v239 offset:38912
	ds_read_b128 v[152:155], v239 offset:39936
	ds_read_b128 v[184:187], v168
	ds_read_b128 v[188:191], v168 offset:1024
	ds_read_b128 v[192:195], v168 offset:2048
	ds_read_b128 v[196:199], v168 offset:3072
	ds_read_b128 v[168:171], v180
	ds_read_b128 v[172:175], v180 offset:1024
	ds_read_b128 v[176:179], v180 offset:2048
	ds_read_b128 v[180:183], v180 offset:3072
	global_load_lds_dwordx4 v[204:205], off
	v_lshl_add_u64 v[204:205], v[242:243], 0, v[208:209]
	s_mov_b32 m0, s67
	s_nop 0
	global_load_lds_dwordx4 v[204:205], off
	s_waitcnt vmcnt(8)
	s_waitcnt lgkmcnt(0)
	s_barrier
	s_setprio 1
	s_waitcnt lgkmcnt(0)
	v_mfma_f32_16x16x32_bf16 v[132:135], v[184:187], v[148:151], v[132:135]
	v_mfma_f32_16x16x32_bf16 v[132:135], v[188:191], v[164:167], v[132:135]
	v_mfma_f32_16x16x32_bf16 v[128:131], v[192:195], v[148:151], v[128:131]
	v_mfma_f32_16x16x32_bf16 v[128:131], v[196:199], v[164:167], v[128:131]
	v_mfma_f32_16x16x32_bf16 v[124:127], v[168:171], v[148:151], v[124:127]
	v_mfma_f32_16x16x32_bf16 v[124:127], v[172:175], v[164:167], v[124:127]
	v_mfma_f32_16x16x32_bf16 v[120:123], v[176:179], v[148:151], v[120:123]
	v_mfma_f32_16x16x32_bf16 v[120:123], v[180:183], v[164:167], v[120:123]
	v_mfma_f32_16x16x32_bf16 v[116:119], v[184:187], v[144:147], v[116:119]
	v_mfma_f32_16x16x32_bf16 v[116:119], v[188:191], v[160:163], v[116:119]
	v_mfma_f32_16x16x32_bf16 v[112:115], v[192:195], v[144:147], v[112:115]
	v_mfma_f32_16x16x32_bf16 v[112:115], v[196:199], v[160:163], v[112:115]
	v_mfma_f32_16x16x32_bf16 v[108:111], v[168:171], v[144:147], v[108:111]
	v_mfma_f32_16x16x32_bf16 v[108:111], v[172:175], v[160:163], v[108:111]
	v_mfma_f32_16x16x32_bf16 v[104:107], v[176:179], v[144:147], v[104:107]
	v_mfma_f32_16x16x32_bf16 v[104:107], v[180:183], v[160:163], v[104:107]
	v_mfma_f32_16x16x32_bf16 v[100:103], v[184:187], v[140:143], v[100:103]
	v_mfma_f32_16x16x32_bf16 v[100:103], v[188:191], v[156:159], v[100:103]
	v_mfma_f32_16x16x32_bf16 v[96:99], v[192:195], v[140:143], v[96:99]
	v_mfma_f32_16x16x32_bf16 v[96:99], v[196:199], v[156:159], v[96:99]
	v_mfma_f32_16x16x32_bf16 v[92:95], v[168:171], v[140:143], v[92:95]
	v_mfma_f32_16x16x32_bf16 v[92:95], v[172:175], v[156:159], v[92:95]
	v_mfma_f32_16x16x32_bf16 v[88:91], v[176:179], v[140:143], v[88:91]
	v_mfma_f32_16x16x32_bf16 v[88:91], v[180:183], v[156:159], v[88:91]
	v_mfma_f32_16x16x32_bf16 v[84:87], v[184:187], v[136:139], v[84:87]
	v_mfma_f32_16x16x32_bf16 v[84:87], v[188:191], v[152:155], v[84:87]
	v_mfma_f32_16x16x32_bf16 v[80:83], v[192:195], v[136:139], v[80:83]
	v_mfma_f32_16x16x32_bf16 v[80:83], v[196:199], v[152:155], v[80:83]
	v_mfma_f32_16x16x32_bf16 v[76:79], v[168:171], v[136:139], v[76:79]
	v_mfma_f32_16x16x32_bf16 v[76:79], v[172:175], v[152:155], v[76:79]
	v_mfma_f32_16x16x32_bf16 v[72:75], v[176:179], v[136:139], v[72:75]
	v_mfma_f32_16x16x32_bf16 v[72:75], v[180:183], v[152:155], v[72:75]
	s_setprio 0
	s_barrier
	s_and_b64 vcc, exec, s[50:51]
	s_cbranch_vccnz .LBB0_565
	ds_read_b128 v[148:151], v239 offset:49152
	ds_read_b128 v[164:167], v239 offset:50176
	ds_read_b128 v[144:147], v239 offset:51200
	ds_read_b128 v[160:163], v239 offset:52224
	ds_read_b128 v[140:143], v239 offset:53248
	ds_read_b128 v[156:159], v239 offset:54272
	ds_read_b128 v[136:139], v239 offset:55296
	ds_read_b128 v[152:155], v239 offset:56320
.LBB0_565:
	s_mov_b32 m0, s70
	v_lshl_add_u64 v[204:205], v[226:227], 0, s[0:1]
	s_add_u32 s12, s12, 0x20080
	global_load_lds_dwordx4 v[204:205], off
	v_lshl_add_u64 v[204:205], v[228:229], 0, s[0:1]
	s_mov_b32 m0, s71
	s_addc_u32 s13, s13, 0
	global_load_lds_dwordx4 v[204:205], off
	v_lshl_add_u64 v[204:205], s[12:13], 0, v[4:5]
	s_mov_b32 m0, s74
	s_and_b64 vcc, exec, s[50:51]
	global_load_lds_dwordx4 v[204:205], off
	v_lshl_add_u64 v[204:205], s[12:13], 0, v[208:209]
	s_mov_b32 m0, s75
	s_nop 0
	global_load_lds_dwordx4 v[204:205], off
	v_lshl_add_u64 v[204:205], v[230:231], 0, s[0:1]
	s_mov_b32 m0, s72
	s_nop 0
	global_load_lds_dwordx4 v[204:205], off
	v_lshl_add_u64 v[204:205], v[232:233], 0, s[0:1]
	s_mov_b32 m0, s73
	s_nop 0
	global_load_lds_dwordx4 v[204:205], off
	s_waitcnt vmcnt(8)
	s_waitcnt lgkmcnt(0)
	s_barrier
	s_cbranch_vccnz .LBB0_558
	s_setprio 1
	s_waitcnt lgkmcnt(0)
	v_mfma_f32_16x16x32_bf16 v[68:71], v[184:187], v[148:151], v[68:71]
	v_mfma_f32_16x16x32_bf16 v[68:71], v[188:191], v[164:167], v[68:71]
	v_mfma_f32_16x16x32_bf16 v[64:67], v[192:195], v[148:151], v[64:67]
	v_mfma_f32_16x16x32_bf16 v[64:67], v[196:199], v[164:167], v[64:67]
	v_mfma_f32_16x16x32_bf16 v[60:63], v[168:171], v[148:151], v[60:63]
	v_mfma_f32_16x16x32_bf16 v[60:63], v[172:175], v[164:167], v[60:63]
	v_mfma_f32_16x16x32_bf16 v[56:59], v[176:179], v[148:151], v[56:59]
	v_mfma_f32_16x16x32_bf16 v[56:59], v[180:183], v[164:167], v[56:59]
	v_mfma_f32_16x16x32_bf16 v[52:55], v[184:187], v[144:147], v[52:55]
	v_mfma_f32_16x16x32_bf16 v[52:55], v[188:191], v[160:163], v[52:55]
	v_mfma_f32_16x16x32_bf16 v[48:51], v[192:195], v[144:147], v[48:51]
	v_mfma_f32_16x16x32_bf16 v[48:51], v[196:199], v[160:163], v[48:51]
	v_mfma_f32_16x16x32_bf16 v[44:47], v[168:171], v[144:147], v[44:47]
	v_mfma_f32_16x16x32_bf16 v[44:47], v[172:175], v[160:163], v[44:47]
	v_mfma_f32_16x16x32_bf16 v[40:43], v[176:179], v[144:147], v[40:43]
	v_mfma_f32_16x16x32_bf16 v[40:43], v[180:183], v[160:163], v[40:43]
	v_mfma_f32_16x16x32_bf16 v[36:39], v[184:187], v[140:143], v[36:39]
	v_mfma_f32_16x16x32_bf16 v[36:39], v[188:191], v[156:159], v[36:39]
	v_mfma_f32_16x16x32_bf16 v[32:35], v[192:195], v[140:143], v[32:35]
	v_mfma_f32_16x16x32_bf16 v[32:35], v[196:199], v[156:159], v[32:35]
	v_mfma_f32_16x16x32_bf16 v[28:31], v[168:171], v[140:143], v[28:31]
	v_mfma_f32_16x16x32_bf16 v[28:31], v[172:175], v[156:159], v[28:31]
	v_mfma_f32_16x16x32_bf16 v[24:27], v[176:179], v[140:143], v[24:27]
	v_mfma_f32_16x16x32_bf16 v[24:27], v[180:183], v[156:159], v[24:27]
	v_mfma_f32_16x16x32_bf16 v[20:23], v[184:187], v[136:139], v[20:23]
	v_mfma_f32_16x16x32_bf16 v[20:23], v[188:191], v[152:155], v[20:23]
	v_mfma_f32_16x16x32_bf16 v[16:19], v[192:195], v[136:139], v[16:19]
	v_mfma_f32_16x16x32_bf16 v[16:19], v[196:199], v[152:155], v[16:19]
	v_mfma_f32_16x16x32_bf16 v[12:15], v[168:171], v[136:139], v[12:15]
	v_mfma_f32_16x16x32_bf16 v[12:15], v[172:175], v[152:155], v[12:15]
	v_mfma_f32_16x16x32_bf16 v[8:11], v[176:179], v[136:139], v[8:11]
	v_mfma_f32_16x16x32_bf16 v[8:11], v[180:183], v[152:155], v[8:11]
	s_setprio 0
	s_branch .LBB0_558

.LBB0_620:
	s_add_u32 s12, s42, 0xfffe0080
	s_addc_u32 s13, s43, -1
	s_cmp_eq_u32 s57, 4
	s_cselect_b32 s15, s17, s13
	s_cselect_b32 s14, s33, s12
	s_cselect_b32 s13, s11, s27
	s_cselect_b32 s12, s37, s26
	s_add_i32 s58, 0, 0x10000
	v_add_u32_e32 v136, s58, v1
	s_add_i32 s60, 0, 0x14000
	ds_read_b128 v[150:153], v7
	ds_read_b128 v[154:157], v7 offset:1024
	ds_read_b128 v[158:161], v7 offset:2048
	ds_read_b128 v[162:165], v7 offset:3072
	ds_read_b128 v[166:169], v7 offset:4096
	ds_read_b128 v[170:173], v7 offset:5120
	ds_read_b128 v[174:177], v7 offset:6144
	ds_read_b128 v[178:181], v7 offset:7168
	ds_read_b128 v[182:185], v136
	ds_read_b128 v[186:189], v136 offset:1024
	ds_read_b128 v[190:193], v136 offset:2048
	ds_read_b128 v[194:197], v136 offset:3072
	v_add_u32_e32 v136, s60, v1
	ds_read_b128 v[208:211], v136
	ds_read_b128 v[212:215], v136 offset:1024
	ds_read_b128 v[216:219], v136 offset:2048
	ds_read_b128 v[220:223], v136 offset:3072
	v_lshl_add_u64 v[136:137], s[42:43], 0, v[146:147]
	s_add_i32 m0, s38, 0xc000
	s_nop 0
	global_load_lds_dwordx4 v[136:137], off
	v_lshl_add_u64 v[136:137], s[42:43], 0, v[148:149]
	s_add_i32 m0, s38, 0xe000
	s_nop 0
	global_load_lds_dwordx4 v[136:137], off
	s_waitcnt vmcnt(8)
	s_waitcnt lgkmcnt(0)
	s_barrier
	s_setprio 1
	s_waitcnt lgkmcnt(0)
	v_mfma_f32_16x16x32_bf16 v[132:135], v[182:185], v[150:153], v[132:135]
	v_mfma_f32_16x16x32_bf16 v[132:135], v[186:189], v[154:157], v[132:135]
	v_mfma_f32_16x16x32_bf16 v[128:131], v[190:193], v[150:153], v[128:131]
	v_mfma_f32_16x16x32_bf16 v[128:131], v[194:197], v[154:157], v[128:131]
	v_mfma_f32_16x16x32_bf16 v[112:115], v[208:211], v[150:153], v[112:115]
	v_mfma_f32_16x16x32_bf16 v[112:115], v[212:215], v[154:157], v[112:115]
	v_mfma_f32_16x16x32_bf16 v[104:107], v[216:219], v[150:153], v[104:107]
	v_mfma_f32_16x16x32_bf16 v[104:107], v[220:223], v[154:157], v[104:107]
	v_mfma_f32_16x16x32_bf16 v[124:127], v[182:185], v[158:161], v[124:127]
	v_mfma_f32_16x16x32_bf16 v[124:127], v[186:189], v[162:165], v[124:127]
	v_mfma_f32_16x16x32_bf16 v[120:123], v[190:193], v[158:161], v[120:123]
	v_mfma_f32_16x16x32_bf16 v[120:123], v[194:197], v[162:165], v[120:123]
	v_mfma_f32_16x16x32_bf16 v[96:99], v[208:211], v[158:161], v[96:99]
	v_mfma_f32_16x16x32_bf16 v[96:99], v[212:215], v[162:165], v[96:99]
	v_mfma_f32_16x16x32_bf16 v[88:91], v[216:219], v[158:161], v[88:91]
	v_mfma_f32_16x16x32_bf16 v[88:91], v[220:223], v[162:165], v[88:91]
	v_mfma_f32_16x16x32_bf16 v[116:119], v[182:185], v[166:169], v[116:119]
	v_mfma_f32_16x16x32_bf16 v[116:119], v[186:189], v[170:173], v[116:119]
	v_mfma_f32_16x16x32_bf16 v[108:111], v[190:193], v[166:169], v[108:111]
	v_mfma_f32_16x16x32_bf16 v[108:111], v[194:197], v[170:173], v[108:111]
	v_mfma_f32_16x16x32_bf16 v[84:87], v[208:211], v[166:169], v[84:87]
	v_mfma_f32_16x16x32_bf16 v[84:87], v[212:215], v[170:173], v[84:87]
	v_mfma_f32_16x16x32_bf16 v[80:83], v[216:219], v[166:169], v[80:83]
	v_mfma_f32_16x16x32_bf16 v[80:83], v[220:223], v[170:173], v[80:83]
	v_mfma_f32_16x16x32_bf16 v[100:103], v[182:185], v[174:177], v[100:103]
	v_mfma_f32_16x16x32_bf16 v[100:103], v[186:189], v[178:181], v[100:103]
	v_mfma_f32_16x16x32_bf16 v[92:95], v[190:193], v[174:177], v[92:95]
	v_mfma_f32_16x16x32_bf16 v[92:95], v[194:197], v[178:181], v[92:95]
	v_mfma_f32_16x16x32_bf16 v[76:79], v[208:211], v[174:177], v[76:79]
	v_mfma_f32_16x16x32_bf16 v[76:79], v[212:215], v[178:181], v[76:79]
	v_mfma_f32_16x16x32_bf16 v[72:75], v[216:219], v[174:177], v[72:75]
	v_mfma_f32_16x16x32_bf16 v[72:75], v[220:223], v[178:181], v[72:75]
	s_setprio 0
	s_barrier
	s_add_i32 s58, s58, s35
	v_lshl_add_u64 v[136:137], s[12:13], 0, v[2:3]
	s_mov_b32 m0, s58
	ds_read_b128 v[150:153], v7 offset:16384
	ds_read_b128 v[154:157], v7 offset:17408
	ds_read_b128 v[158:161], v7 offset:18432
	ds_read_b128 v[162:165], v7 offset:19456
	ds_read_b128 v[166:169], v7 offset:20480
	ds_read_b128 v[170:173], v7 offset:21504
	ds_read_b128 v[174:177], v7 offset:22528
	ds_read_b128 v[178:181], v7 offset:23552
	global_load_lds_dwordx4 v[136:137], off
	s_add_i32 m0, s58, 0x2000
	s_add_u32 s58, s12, 0x20000
	v_lshl_add_u64 v[198:199], s[12:13], 0, v[4:5]
	s_addc_u32 s59, s13, 0
	s_add_i32 s60, s60, s35
	global_load_lds_dwordx4 v[198:199], off
	v_lshl_add_u64 v[204:205], s[58:59], 0, v[2:3]
	s_mov_b32 m0, s60
	v_lshl_add_u64 v[224:225], s[14:15], 0, v[138:139]
	global_load_lds_dwordx4 v[204:205], off
	v_lshl_add_u64 v[204:205], s[58:59], 0, v[4:5]
	s_add_i32 m0, s60, 0x2000
	s_nop 0
	global_load_lds_dwordx4 v[204:205], off
	v_lshl_add_u64 v[204:205], s[14:15], 0, v[140:141]
	s_mov_b32 m0, s38
	s_nop 0
	global_load_lds_dwordx4 v[204:205], off
	s_mov_b32 m0, s39
	s_nop 0
	global_load_lds_dwordx4 v[224:225], off
	s_waitcnt vmcnt(8)
	s_waitcnt lgkmcnt(0)
	s_barrier
	s_setprio 1
	s_waitcnt lgkmcnt(0)
	v_mfma_f32_16x16x32_bf16 v[68:71], v[182:185], v[150:153], v[68:71]
	v_mfma_f32_16x16x32_bf16 v[68:71], v[186:189], v[154:157], v[68:71]
	v_mfma_f32_16x16x32_bf16 v[64:67], v[190:193], v[150:153], v[64:67]
	v_mfma_f32_16x16x32_bf16 v[64:67], v[194:197], v[154:157], v[64:67]
	v_mfma_f32_16x16x32_bf16 v[48:51], v[208:211], v[150:153], v[48:51]
	v_mfma_f32_16x16x32_bf16 v[48:51], v[212:215], v[154:157], v[48:51]
	v_mfma_f32_16x16x32_bf16 v[40:43], v[216:219], v[150:153], v[40:43]
	v_mfma_f32_16x16x32_bf16 v[40:43], v[220:223], v[154:157], v[40:43]
	v_mfma_f32_16x16x32_bf16 v[60:63], v[182:185], v[158:161], v[60:63]
	v_mfma_f32_16x16x32_bf16 v[60:63], v[186:189], v[162:165], v[60:63]
	v_mfma_f32_16x16x32_bf16 v[56:59], v[190:193], v[158:161], v[56:59]
	v_mfma_f32_16x16x32_bf16 v[56:59], v[194:197], v[162:165], v[56:59]
	v_mfma_f32_16x16x32_bf16 v[32:35], v[208:211], v[158:161], v[32:35]
	v_mfma_f32_16x16x32_bf16 v[32:35], v[212:215], v[162:165], v[32:35]
	v_mfma_f32_16x16x32_bf16 v[24:27], v[216:219], v[158:161], v[24:27]
	v_mfma_f32_16x16x32_bf16 v[24:27], v[220:223], v[162:165], v[24:27]
	v_mfma_f32_16x16x32_bf16 v[52:55], v[182:185], v[166:169], v[52:55]
	v_mfma_f32_16x16x32_bf16 v[52:55], v[186:189], v[170:173], v[52:55]
	v_mfma_f32_16x16x32_bf16 v[44:47], v[190:193], v[166:169], v[44:47]
	v_mfma_f32_16x16x32_bf16 v[44:47], v[194:197], v[170:173], v[44:47]
	v_mfma_f32_16x16x32_bf16 v[20:23], v[208:211], v[166:169], v[20:23]
	v_mfma_f32_16x16x32_bf16 v[20:23], v[212:215], v[170:173], v[20:23]
	v_mfma_f32_16x16x32_bf16 v[16:19], v[216:219], v[166:169], v[16:19]
	v_mfma_f32_16x16x32_bf16 v[16:19], v[220:223], v[170:173], v[16:19]
	v_mfma_f32_16x16x32_bf16 v[36:39], v[182:185], v[174:177], v[36:39]
	v_mfma_f32_16x16x32_bf16 v[36:39], v[186:189], v[178:181], v[36:39]
	v_mfma_f32_16x16x32_bf16 v[28:31], v[190:193], v[174:177], v[28:31]
	v_mfma_f32_16x16x32_bf16 v[28:31], v[194:197], v[178:181], v[28:31]
	v_mfma_f32_16x16x32_bf16 v[12:15], v[208:211], v[174:177], v[12:15]
	v_mfma_f32_16x16x32_bf16 v[12:15], v[212:215], v[178:181], v[12:15]
	v_mfma_f32_16x16x32_bf16 v[8:11], v[216:219], v[174:177], v[8:11]
	v_mfma_f32_16x16x32_bf16 v[8:11], v[220:223], v[178:181], v[8:11]
	s_setprio 0
	s_barrier
	s_add_i32 s58, 0, 0x18000
	s_add_i32 s59, 0, 0x1c000
	s_add_u32 s14, s14, 0x20000
	s_addc_u32 s15, s15, 0
	s_mov_b32 m0, s40
	v_add_u32_e32 v194, s58, v1
	v_add_u32_e32 v207, s59, v1
	v_lshl_add_u64 v[226:227], s[14:15], 0, v[140:141]
	ds_read_b128 v[150:153], v7 offset:32768
	ds_read_b128 v[154:157], v7 offset:33792
	ds_read_b128 v[158:161], v7 offset:34816
	ds_read_b128 v[162:165], v7 offset:35840
	ds_read_b128 v[166:169], v7 offset:36864
	ds_read_b128 v[170:173], v7 offset:37888
	ds_read_b128 v[174:177], v7 offset:38912
	ds_read_b128 v[178:181], v7 offset:39936
	ds_read_b128 v[182:185], v194
	ds_read_b128 v[186:189], v194 offset:1024
	ds_read_b128 v[190:193], v194 offset:2048
	ds_read_b128 v[194:197], v194 offset:3072
	ds_read_b128 v[208:211], v207
	ds_read_b128 v[212:215], v207 offset:1024
	ds_read_b128 v[216:219], v207 offset:2048
	ds_read_b128 v[220:223], v207 offset:3072
	global_load_lds_dwordx4 v[226:227], off
	v_lshl_add_u64 v[226:227], s[14:15], 0, v[138:139]
	s_mov_b32 m0, s41
	s_nop 0
	global_load_lds_dwordx4 v[226:227], off
	s_waitcnt vmcnt(8)
	s_waitcnt lgkmcnt(0)
	s_barrier
	s_setprio 1
	s_waitcnt lgkmcnt(0)
	v_mfma_f32_16x16x32_bf16 v[132:135], v[182:185], v[150:153], v[132:135]
	v_mfma_f32_16x16x32_bf16 v[132:135], v[186:189], v[154:157], v[132:135]
	v_mfma_f32_16x16x32_bf16 v[128:131], v[190:193], v[150:153], v[128:131]
	v_mfma_f32_16x16x32_bf16 v[128:131], v[194:197], v[154:157], v[128:131]
	v_mfma_f32_16x16x32_bf16 v[112:115], v[208:211], v[150:153], v[112:115]
	v_mfma_f32_16x16x32_bf16 v[112:115], v[212:215], v[154:157], v[112:115]
	v_mfma_f32_16x16x32_bf16 v[104:107], v[216:219], v[150:153], v[104:107]
	v_mfma_f32_16x16x32_bf16 v[104:107], v[220:223], v[154:157], v[104:107]
	v_mfma_f32_16x16x32_bf16 v[124:127], v[182:185], v[158:161], v[124:127]
	v_mfma_f32_16x16x32_bf16 v[124:127], v[186:189], v[162:165], v[124:127]
	v_mfma_f32_16x16x32_bf16 v[120:123], v[190:193], v[158:161], v[120:123]
	v_mfma_f32_16x16x32_bf16 v[120:123], v[194:197], v[162:165], v[120:123]
	v_mfma_f32_16x16x32_bf16 v[96:99], v[208:211], v[158:161], v[96:99]
	v_mfma_f32_16x16x32_bf16 v[96:99], v[212:215], v[162:165], v[96:99]
	v_mfma_f32_16x16x32_bf16 v[88:91], v[216:219], v[158:161], v[88:91]
	v_mfma_f32_16x16x32_bf16 v[88:91], v[220:223], v[162:165], v[88:91]
	v_mfma_f32_16x16x32_bf16 v[116:119], v[182:185], v[166:169], v[116:119]
	v_mfma_f32_16x16x32_bf16 v[116:119], v[186:189], v[170:173], v[116:119]
	v_mfma_f32_16x16x32_bf16 v[108:111], v[190:193], v[166:169], v[108:111]
	v_mfma_f32_16x16x32_bf16 v[108:111], v[194:197], v[170:173], v[108:111]
	v_mfma_f32_16x16x32_bf16 v[84:87], v[208:211], v[166:169], v[84:87]
	v_mfma_f32_16x16x32_bf16 v[84:87], v[212:215], v[170:173], v[84:87]
	v_mfma_f32_16x16x32_bf16 v[80:83], v[216:219], v[166:169], v[80:83]
	v_mfma_f32_16x16x32_bf16 v[80:83], v[220:223], v[170:173], v[80:83]
	v_mfma_f32_16x16x32_bf16 v[100:103], v[182:185], v[174:177], v[100:103]
	v_mfma_f32_16x16x32_bf16 v[100:103], v[186:189], v[178:181], v[100:103]
	v_mfma_f32_16x16x32_bf16 v[92:95], v[190:193], v[174:177], v[92:95]
	v_mfma_f32_16x16x32_bf16 v[92:95], v[194:197], v[178:181], v[92:95]
	v_mfma_f32_16x16x32_bf16 v[76:79], v[208:211], v[174:177], v[76:79]
	v_mfma_f32_16x16x32_bf16 v[76:79], v[212:215], v[178:181], v[76:79]
	v_mfma_f32_16x16x32_bf16 v[72:75], v[216:219], v[174:177], v[72:75]
	v_mfma_f32_16x16x32_bf16 v[72:75], v[220:223], v[178:181], v[72:75]
	s_setprio 0
	s_barrier
	s_add_i32 s14, s58, s35
	v_lshl_add_u64 v[136:137], v[136:137], 0, s[0:1]
	s_mov_b32 m0, s14
	ds_read_b128 v[150:153], v7 offset:49152
	ds_read_b128 v[154:157], v7 offset:50176
	ds_read_b128 v[158:161], v7 offset:51200
	ds_read_b128 v[162:165], v7 offset:52224
	ds_read_b128 v[166:169], v7 offset:53248
	ds_read_b128 v[170:173], v7 offset:54272
	ds_read_b128 v[174:177], v7 offset:55296
	ds_read_b128 v[178:181], v7 offset:56320
	global_load_lds_dwordx4 v[136:137], off
	s_add_i32 m0, s14, 0x2000
	s_add_u32 s12, s12, 0x20080
	v_lshl_add_u64 v[136:137], v[198:199], 0, s[0:1]
	s_addc_u32 s13, s13, 0
	s_add_i32 s14, s59, s35
	global_load_lds_dwordx4 v[136:137], off
	v_lshl_add_u64 v[136:137], s[12:13], 0, v[2:3]
	s_mov_b32 m0, s14
	s_nop 0
	global_load_lds_dwordx4 v[136:137], off
	v_lshl_add_u64 v[136:137], s[12:13], 0, v[4:5]
	s_add_i32 m0, s14, 0x2000
	s_nop 0
	global_load_lds_dwordx4 v[136:137], off
	v_lshl_add_u64 v[136:137], v[204:205], 0, s[0:1]
	s_mov_b32 m0, s49
	s_nop 0
	global_load_lds_dwordx4 v[136:137], off
	v_lshl_add_u64 v[136:137], v[224:225], 0, s[0:1]
	s_mov_b32 m0, s52
	s_nop 0
	global_load_lds_dwordx4 v[136:137], off
	s_waitcnt vmcnt(8)
	s_waitcnt lgkmcnt(0)
	s_barrier
	s_setprio 1
	s_waitcnt lgkmcnt(0)
	v_mfma_f32_16x16x32_bf16 v[68:71], v[182:185], v[150:153], v[68:71]
	v_mfma_f32_16x16x32_bf16 v[68:71], v[186:189], v[154:157], v[68:71]
	v_mfma_f32_16x16x32_bf16 v[64:67], v[190:193], v[150:153], v[64:67]
	v_mfma_f32_16x16x32_bf16 v[64:67], v[194:197], v[154:157], v[64:67]
	v_mfma_f32_16x16x32_bf16 v[48:51], v[208:211], v[150:153], v[48:51]
	v_mfma_f32_16x16x32_bf16 v[48:51], v[212:215], v[154:157], v[48:51]
	v_mfma_f32_16x16x32_bf16 v[40:43], v[216:219], v[150:153], v[40:43]
	v_mfma_f32_16x16x32_bf16 v[40:43], v[220:223], v[154:157], v[40:43]
	v_mfma_f32_16x16x32_bf16 v[60:63], v[182:185], v[158:161], v[60:63]
	v_mfma_f32_16x16x32_bf16 v[60:63], v[186:189], v[162:165], v[60:63]
	v_mfma_f32_16x16x32_bf16 v[56:59], v[190:193], v[158:161], v[56:59]
	v_mfma_f32_16x16x32_bf16 v[56:59], v[194:197], v[162:165], v[56:59]
	v_mfma_f32_16x16x32_bf16 v[32:35], v[208:211], v[158:161], v[32:35]
	v_mfma_f32_16x16x32_bf16 v[32:35], v[212:215], v[162:165], v[32:35]
	v_mfma_f32_16x16x32_bf16 v[24:27], v[216:219], v[158:161], v[24:27]
	v_mfma_f32_16x16x32_bf16 v[24:27], v[220:223], v[162:165], v[24:27]
	v_mfma_f32_16x16x32_bf16 v[52:55], v[182:185], v[166:169], v[52:55]
	v_mfma_f32_16x16x32_bf16 v[52:55], v[186:189], v[170:173], v[52:55]
	v_mfma_f32_16x16x32_bf16 v[44:47], v[190:193], v[166:169], v[44:47]
	v_mfma_f32_16x16x32_bf16 v[44:47], v[194:197], v[170:173], v[44:47]
	v_mfma_f32_16x16x32_bf16 v[20:23], v[208:211], v[166:169], v[20:23]
	v_mfma_f32_16x16x32_bf16 v[20:23], v[212:215], v[170:173], v[20:23]
	v_mfma_f32_16x16x32_bf16 v[16:19], v[216:219], v[166:169], v[16:19]
	v_mfma_f32_16x16x32_bf16 v[16:19], v[220:223], v[170:173], v[16:19]
	v_mfma_f32_16x16x32_bf16 v[36:39], v[182:185], v[174:177], v[36:39]
	v_mfma_f32_16x16x32_bf16 v[36:39], v[186:189], v[178:181], v[36:39]
	v_mfma_f32_16x16x32_bf16 v[28:31], v[190:193], v[174:177], v[28:31]
	v_mfma_f32_16x16x32_bf16 v[28:31], v[194:197], v[178:181], v[28:31]
	v_mfma_f32_16x16x32_bf16 v[12:15], v[208:211], v[174:177], v[12:15]
	v_mfma_f32_16x16x32_bf16 v[12:15], v[212:215], v[178:181], v[12:15]
	v_mfma_f32_16x16x32_bf16 v[8:11], v[216:219], v[174:177], v[8:11]
	v_mfma_f32_16x16x32_bf16 v[8:11], v[220:223], v[178:181], v[8:11]
	s_setprio 0
	s_barrier
	s_add_i32 s57, s57, 2
	s_add_u32 s42, s42, 0x100
	s_addc_u32 s43, s43, 0
	s_add_u32 s26, s26, 0x100
	s_addc_u32 s27, s27, 0
	s_cmp_gt_u32 s57, 5
	s_cbranch_scc0 .LBB0_620
	s_and_b64 vcc, exec, s[6:7]
	s_cbranch_vccz .LBB0_623
	s_barrier

.LBB0_986:
	s_add_u32 s12, s44, 0xfff80080
	s_addc_u32 s13, s45, -1
	s_cmp_eq_u32 s50, 28
	s_cselect_b32 s15, s18, s13
	s_cselect_b32 s14, s19, s12
	s_cselect_b32 s13, s17, s43
	s_cselect_b32 s12, s21, s33
	s_add_i32 s51, 0, 0x10000
	v_add_u32_e32 v2, s51, v7
	s_add_i32 s63, 0, 0x14000
	ds_read_b128 v[150:153], v155
	ds_read_b128 v[156:159], v155 offset:1024
	ds_read_b128 v[160:163], v155 offset:2048
	ds_read_b128 v[164:167], v155 offset:3072
	ds_read_b128 v[168:171], v155 offset:4096
	ds_read_b128 v[172:175], v155 offset:5120
	ds_read_b128 v[176:179], v155 offset:6144
	ds_read_b128 v[180:183], v155 offset:7168
	ds_read_b128 v[184:187], v2
	ds_read_b128 v[188:191], v2 offset:1024
	ds_read_b128 v[192:195], v2 offset:2048
	ds_read_b128 v[196:199], v2 offset:3072
	v_add_u32_e32 v2, s63, v7
	v_lshl_add_u64 v[224:225], s[44:45], 0, v[146:147]
	s_add_i32 m0, s39, 0xc000
	ds_read_b128 v[208:211], v2
	ds_read_b128 v[212:215], v2 offset:1024
	ds_read_b128 v[216:219], v2 offset:2048
	ds_read_b128 v[220:223], v2 offset:3072
	global_load_lds_dwordx4 v[224:225], off
	v_lshl_add_u64 v[224:225], s[44:45], 0, v[148:149]
	s_add_i32 m0, s39, 0xe000
	s_nop 0
	global_load_lds_dwordx4 v[224:225], off
	s_waitcnt vmcnt(8)
	s_waitcnt lgkmcnt(0)
	s_barrier
	s_setprio 1
	s_waitcnt lgkmcnt(0)
	v_mfma_f32_16x16x32_bf16 v[132:135], v[184:187], v[150:153], v[132:135]
	v_mfma_f32_16x16x32_bf16 v[132:135], v[188:191], v[156:159], v[132:135]
	v_mfma_f32_16x16x32_bf16 v[128:131], v[192:195], v[150:153], v[128:131]
	v_mfma_f32_16x16x32_bf16 v[128:131], v[196:199], v[156:159], v[128:131]
	v_mfma_f32_16x16x32_bf16 v[124:127], v[208:211], v[150:153], v[124:127]
	v_mfma_f32_16x16x32_bf16 v[124:127], v[212:215], v[156:159], v[124:127]
	v_mfma_f32_16x16x32_bf16 v[120:123], v[216:219], v[150:153], v[120:123]
	v_mfma_f32_16x16x32_bf16 v[120:123], v[220:223], v[156:159], v[120:123]
	v_mfma_f32_16x16x32_bf16 v[116:119], v[184:187], v[160:163], v[116:119]
	v_mfma_f32_16x16x32_bf16 v[116:119], v[188:191], v[164:167], v[116:119]
	v_mfma_f32_16x16x32_bf16 v[112:115], v[192:195], v[160:163], v[112:115]
	v_mfma_f32_16x16x32_bf16 v[112:115], v[196:199], v[164:167], v[112:115]
	v_mfma_f32_16x16x32_bf16 v[108:111], v[208:211], v[160:163], v[108:111]
	v_mfma_f32_16x16x32_bf16 v[108:111], v[212:215], v[164:167], v[108:111]
	v_mfma_f32_16x16x32_bf16 v[104:107], v[216:219], v[160:163], v[104:107]
	v_mfma_f32_16x16x32_bf16 v[104:107], v[220:223], v[164:167], v[104:107]
	v_mfma_f32_16x16x32_bf16 v[100:103], v[184:187], v[168:171], v[100:103]
	v_mfma_f32_16x16x32_bf16 v[100:103], v[188:191], v[172:175], v[100:103]
	v_mfma_f32_16x16x32_bf16 v[96:99], v[192:195], v[168:171], v[96:99]
	v_mfma_f32_16x16x32_bf16 v[96:99], v[196:199], v[172:175], v[96:99]
	v_mfma_f32_16x16x32_bf16 v[92:95], v[208:211], v[168:171], v[92:95]
	v_mfma_f32_16x16x32_bf16 v[92:95], v[212:215], v[172:175], v[92:95]
	v_mfma_f32_16x16x32_bf16 v[88:91], v[216:219], v[168:171], v[88:91]
	v_mfma_f32_16x16x32_bf16 v[88:91], v[220:223], v[172:175], v[88:91]
	v_mfma_f32_16x16x32_bf16 v[84:87], v[184:187], v[176:179], v[84:87]
	v_mfma_f32_16x16x32_bf16 v[84:87], v[188:191], v[180:183], v[84:87]
	v_mfma_f32_16x16x32_bf16 v[80:83], v[192:195], v[176:179], v[80:83]
	v_mfma_f32_16x16x32_bf16 v[80:83], v[196:199], v[180:183], v[80:83]
	v_mfma_f32_16x16x32_bf16 v[76:79], v[208:211], v[176:179], v[76:79]
	v_mfma_f32_16x16x32_bf16 v[76:79], v[212:215], v[180:183], v[76:79]
	v_mfma_f32_16x16x32_bf16 v[72:75], v[216:219], v[176:179], v[72:75]
	v_mfma_f32_16x16x32_bf16 v[72:75], v[220:223], v[180:183], v[72:75]
	s_setprio 0
	s_barrier
	s_add_i32 s51, s51, s38
	v_lshl_add_u64 v[224:225], s[12:13], 0, v[138:139]
	s_mov_b32 m0, s51
	ds_read_b128 v[150:153], v155 offset:16384
	ds_read_b128 v[156:159], v155 offset:17408
	ds_read_b128 v[160:163], v155 offset:18432
	ds_read_b128 v[164:167], v155 offset:19456
	ds_read_b128 v[168:171], v155 offset:20480
	ds_read_b128 v[172:175], v155 offset:21504
	ds_read_b128 v[176:179], v155 offset:22528
	ds_read_b128 v[180:183], v155 offset:23552
	global_load_lds_dwordx4 v[224:225], off
	s_add_i32 m0, s51, 0x2000
	s_add_u32 s64, s12, 0x80000
	v_lshl_add_u64 v[226:227], s[12:13], 0, v[4:5]
	s_addc_u32 s65, s13, 0
	s_add_i32 s51, s63, s38
	global_load_lds_dwordx4 v[226:227], off
	v_lshl_add_u64 v[228:229], s[64:65], 0, v[138:139]
	s_mov_b32 m0, s51
	v_lshl_add_u64 v[230:231], s[14:15], 0, v[136:137]
	global_load_lds_dwordx4 v[228:229], off
	v_lshl_add_u64 v[228:229], s[64:65], 0, v[4:5]
	s_add_i32 m0, s51, 0x2000
	s_nop 0
	global_load_lds_dwordx4 v[228:229], off
	v_lshl_add_u64 v[228:229], s[14:15], 0, v[140:141]
	s_mov_b32 m0, s39
	s_nop 0
	global_load_lds_dwordx4 v[228:229], off
	s_mov_b32 m0, s40
	s_nop 0
	global_load_lds_dwordx4 v[230:231], off
	s_waitcnt vmcnt(8)
	s_waitcnt lgkmcnt(0)
	s_barrier
	s_setprio 1
	s_waitcnt lgkmcnt(0)
	v_mfma_f32_16x16x32_bf16 v[68:71], v[184:187], v[150:153], v[68:71]
	v_mfma_f32_16x16x32_bf16 v[68:71], v[188:191], v[156:159], v[68:71]
	v_mfma_f32_16x16x32_bf16 v[64:67], v[192:195], v[150:153], v[64:67]
	v_mfma_f32_16x16x32_bf16 v[64:67], v[196:199], v[156:159], v[64:67]
	v_mfma_f32_16x16x32_bf16 v[60:63], v[208:211], v[150:153], v[60:63]
	v_mfma_f32_16x16x32_bf16 v[60:63], v[212:215], v[156:159], v[60:63]
	v_mfma_f32_16x16x32_bf16 v[56:59], v[216:219], v[150:153], v[56:59]
	v_mfma_f32_16x16x32_bf16 v[56:59], v[220:223], v[156:159], v[56:59]
	v_mfma_f32_16x16x32_bf16 v[52:55], v[184:187], v[160:163], v[52:55]
	v_mfma_f32_16x16x32_bf16 v[52:55], v[188:191], v[164:167], v[52:55]
	v_mfma_f32_16x16x32_bf16 v[48:51], v[192:195], v[160:163], v[48:51]
	v_mfma_f32_16x16x32_bf16 v[48:51], v[196:199], v[164:167], v[48:51]
	v_mfma_f32_16x16x32_bf16 v[44:47], v[208:211], v[160:163], v[44:47]
	v_mfma_f32_16x16x32_bf16 v[44:47], v[212:215], v[164:167], v[44:47]
	v_mfma_f32_16x16x32_bf16 v[40:43], v[216:219], v[160:163], v[40:43]
	v_mfma_f32_16x16x32_bf16 v[40:43], v[220:223], v[164:167], v[40:43]
	v_mfma_f32_16x16x32_bf16 v[36:39], v[184:187], v[168:171], v[36:39]
	v_mfma_f32_16x16x32_bf16 v[36:39], v[188:191], v[172:175], v[36:39]
	v_mfma_f32_16x16x32_bf16 v[32:35], v[192:195], v[168:171], v[32:35]
	v_mfma_f32_16x16x32_bf16 v[32:35], v[196:199], v[172:175], v[32:35]
	v_mfma_f32_16x16x32_bf16 v[28:31], v[208:211], v[168:171], v[28:31]
	v_mfma_f32_16x16x32_bf16 v[28:31], v[212:215], v[172:175], v[28:31]
	v_mfma_f32_16x16x32_bf16 v[24:27], v[216:219], v[168:171], v[24:27]
	v_mfma_f32_16x16x32_bf16 v[24:27], v[220:223], v[172:175], v[24:27]
	v_mfma_f32_16x16x32_bf16 v[20:23], v[184:187], v[176:179], v[20:23]
	v_mfma_f32_16x16x32_bf16 v[20:23], v[188:191], v[180:183], v[20:23]
	v_mfma_f32_16x16x32_bf16 v[16:19], v[192:195], v[176:179], v[16:19]
	v_mfma_f32_16x16x32_bf16 v[16:19], v[196:199], v[180:183], v[16:19]
	v_mfma_f32_16x16x32_bf16 v[12:15], v[208:211], v[176:179], v[12:15]
	v_mfma_f32_16x16x32_bf16 v[12:15], v[212:215], v[180:183], v[12:15]
	v_mfma_f32_16x16x32_bf16 v[8:11], v[216:219], v[176:179], v[8:11]
	v_mfma_f32_16x16x32_bf16 v[8:11], v[220:223], v[180:183], v[8:11]
	s_setprio 0
	s_barrier
	s_add_i32 s51, 0, 0x18000
	s_add_i32 s63, 0, 0x1c000
	s_add_u32 s14, s14, 0x80000
	v_add_u32_e32 v2, s51, v7
	s_addc_u32 s15, s15, 0
	s_mov_b32 m0, s41
	ds_read_b128 v[150:153], v155 offset:32768
	ds_read_b128 v[156:159], v155 offset:33792
	ds_read_b128 v[160:163], v155 offset:34816
	ds_read_b128 v[164:167], v155 offset:35840
	ds_read_b128 v[168:171], v155 offset:36864
	ds_read_b128 v[172:175], v155 offset:37888
	ds_read_b128 v[176:179], v155 offset:38912
	ds_read_b128 v[180:183], v155 offset:39936
	ds_read_b128 v[184:187], v2
	ds_read_b128 v[188:191], v2 offset:1024
	ds_read_b128 v[192:195], v2 offset:2048
	ds_read_b128 v[196:199], v2 offset:3072
	v_add_u32_e32 v2, s63, v7
	v_lshl_add_u64 v[232:233], s[14:15], 0, v[140:141]
	ds_read_b128 v[208:211], v2
	ds_read_b128 v[212:215], v2 offset:1024
	ds_read_b128 v[216:219], v2 offset:2048
	ds_read_b128 v[220:223], v2 offset:3072
	global_load_lds_dwordx4 v[232:233], off
	v_lshl_add_u64 v[232:233], s[14:15], 0, v[136:137]
	s_mov_b32 m0, s47
	s_nop 0
	global_load_lds_dwordx4 v[232:233], off
	s_waitcnt vmcnt(8)
	s_waitcnt lgkmcnt(0)
	s_barrier
	s_setprio 1
	s_waitcnt lgkmcnt(0)
	v_mfma_f32_16x16x32_bf16 v[132:135], v[184:187], v[150:153], v[132:135]
	v_mfma_f32_16x16x32_bf16 v[132:135], v[188:191], v[156:159], v[132:135]
	v_mfma_f32_16x16x32_bf16 v[128:131], v[192:195], v[150:153], v[128:131]
	v_mfma_f32_16x16x32_bf16 v[128:131], v[196:199], v[156:159], v[128:131]
	v_mfma_f32_16x16x32_bf16 v[124:127], v[208:211], v[150:153], v[124:127]
	v_mfma_f32_16x16x32_bf16 v[124:127], v[212:215], v[156:159], v[124:127]
	v_mfma_f32_16x16x32_bf16 v[120:123], v[216:219], v[150:153], v[120:123]
	v_mfma_f32_16x16x32_bf16 v[120:123], v[220:223], v[156:159], v[120:123]
	v_mfma_f32_16x16x32_bf16 v[116:119], v[184:187], v[160:163], v[116:119]
	v_mfma_f32_16x16x32_bf16 v[116:119], v[188:191], v[164:167], v[116:119]
	v_mfma_f32_16x16x32_bf16 v[112:115], v[192:195], v[160:163], v[112:115]
	v_mfma_f32_16x16x32_bf16 v[112:115], v[196:199], v[164:167], v[112:115]
	v_mfma_f32_16x16x32_bf16 v[108:111], v[208:211], v[160:163], v[108:111]
	v_mfma_f32_16x16x32_bf16 v[108:111], v[212:215], v[164:167], v[108:111]
	v_mfma_f32_16x16x32_bf16 v[104:107], v[216:219], v[160:163], v[104:107]
	v_mfma_f32_16x16x32_bf16 v[104:107], v[220:223], v[164:167], v[104:107]
	v_mfma_f32_16x16x32_bf16 v[100:103], v[184:187], v[168:171], v[100:103]
	v_mfma_f32_16x16x32_bf16 v[100:103], v[188:191], v[172:175], v[100:103]
	v_mfma_f32_16x16x32_bf16 v[96:99], v[192:195], v[168:171], v[96:99]
	v_mfma_f32_16x16x32_bf16 v[96:99], v[196:199], v[172:175], v[96:99]
	v_mfma_f32_16x16x32_bf16 v[92:95], v[208:211], v[168:171], v[92:95]
	v_mfma_f32_16x16x32_bf16 v[92:95], v[212:215], v[172:175], v[92:95]
	v_mfma_f32_16x16x32_bf16 v[88:91], v[216:219], v[168:171], v[88:91]
	v_mfma_f32_16x16x32_bf16 v[88:91], v[220:223], v[172:175], v[88:91]
	v_mfma_f32_16x16x32_bf16 v[84:87], v[184:187], v[176:179], v[84:87]
	v_mfma_f32_16x16x32_bf16 v[84:87], v[188:191], v[180:183], v[84:87]
	v_mfma_f32_16x16x32_bf16 v[80:83], v[192:195], v[176:179], v[80:83]
	v_mfma_f32_16x16x32_bf16 v[80:83], v[196:199], v[180:183], v[80:83]
	v_mfma_f32_16x16x32_bf16 v[76:79], v[208:211], v[176:179], v[76:79]
	v_mfma_f32_16x16x32_bf16 v[76:79], v[212:215], v[180:183], v[76:79]
	v_mfma_f32_16x16x32_bf16 v[72:75], v[216:219], v[176:179], v[72:75]
	v_mfma_f32_16x16x32_bf16 v[72:75], v[220:223], v[180:183], v[72:75]
	s_setprio 0
	s_barrier
	s_add_i32 s14, s51, s38
	v_lshl_add_u64 v[224:225], v[224:225], 0, s[0:1]
	s_mov_b32 m0, s14
	ds_read_b128 v[150:153], v155 offset:49152
	ds_read_b128 v[156:159], v155 offset:50176
	ds_read_b128 v[160:163], v155 offset:51200
	ds_read_b128 v[164:167], v155 offset:52224
	ds_read_b128 v[168:171], v155 offset:53248
	ds_read_b128 v[172:175], v155 offset:54272
	ds_read_b128 v[176:179], v155 offset:55296
	ds_read_b128 v[180:183], v155 offset:56320
	global_load_lds_dwordx4 v[224:225], off
	s_add_i32 m0, s14, 0x2000
	s_add_u32 s12, s12, 0x80080
	v_lshl_add_u64 v[224:225], v[226:227], 0, s[0:1]
	s_addc_u32 s13, s13, 0
	s_add_i32 s14, s63, s38
	global_load_lds_dwordx4 v[224:225], off
	v_lshl_add_u64 v[224:225], s[12:13], 0, v[138:139]
	s_mov_b32 m0, s14
	s_nop 0
	global_load_lds_dwordx4 v[224:225], off
	v_lshl_add_u64 v[224:225], s[12:13], 0, v[4:5]
	s_add_i32 m0, s14, 0x2000
	s_nop 0
	global_load_lds_dwordx4 v[224:225], off
	v_lshl_add_u64 v[224:225], v[228:229], 0, s[0:1]
	s_mov_b32 m0, s60
	s_nop 0
	global_load_lds_dwordx4 v[224:225], off
	v_lshl_add_u64 v[224:225], v[230:231], 0, s[0:1]
	s_mov_b32 m0, s61
	s_nop 0
	global_load_lds_dwordx4 v[224:225], off
	s_waitcnt vmcnt(8)
	s_waitcnt lgkmcnt(0)
	s_barrier
	s_setprio 1
	s_waitcnt lgkmcnt(0)
	v_mfma_f32_16x16x32_bf16 v[68:71], v[184:187], v[150:153], v[68:71]
	v_mfma_f32_16x16x32_bf16 v[68:71], v[188:191], v[156:159], v[68:71]
	v_mfma_f32_16x16x32_bf16 v[64:67], v[192:195], v[150:153], v[64:67]
	v_mfma_f32_16x16x32_bf16 v[64:67], v[196:199], v[156:159], v[64:67]
	v_mfma_f32_16x16x32_bf16 v[60:63], v[208:211], v[150:153], v[60:63]
	v_mfma_f32_16x16x32_bf16 v[60:63], v[212:215], v[156:159], v[60:63]
	v_mfma_f32_16x16x32_bf16 v[56:59], v[216:219], v[150:153], v[56:59]
	v_mfma_f32_16x16x32_bf16 v[56:59], v[220:223], v[156:159], v[56:59]
	v_mfma_f32_16x16x32_bf16 v[52:55], v[184:187], v[160:163], v[52:55]
	v_mfma_f32_16x16x32_bf16 v[52:55], v[188:191], v[164:167], v[52:55]
	v_mfma_f32_16x16x32_bf16 v[48:51], v[192:195], v[160:163], v[48:51]
	v_mfma_f32_16x16x32_bf16 v[48:51], v[196:199], v[164:167], v[48:51]
	v_mfma_f32_16x16x32_bf16 v[44:47], v[208:211], v[160:163], v[44:47]
	v_mfma_f32_16x16x32_bf16 v[44:47], v[212:215], v[164:167], v[44:47]
	v_mfma_f32_16x16x32_bf16 v[40:43], v[216:219], v[160:163], v[40:43]
	v_mfma_f32_16x16x32_bf16 v[40:43], v[220:223], v[164:167], v[40:43]
	v_mfma_f32_16x16x32_bf16 v[36:39], v[184:187], v[168:171], v[36:39]
	v_mfma_f32_16x16x32_bf16 v[36:39], v[188:191], v[172:175], v[36:39]
	v_mfma_f32_16x16x32_bf16 v[32:35], v[192:195], v[168:171], v[32:35]
	v_mfma_f32_16x16x32_bf16 v[32:35], v[196:199], v[172:175], v[32:35]
	v_mfma_f32_16x16x32_bf16 v[28:31], v[208:211], v[168:171], v[28:31]
	v_mfma_f32_16x16x32_bf16 v[28:31], v[212:215], v[172:175], v[28:31]
	v_mfma_f32_16x16x32_bf16 v[24:27], v[216:219], v[168:171], v[24:27]
	v_mfma_f32_16x16x32_bf16 v[24:27], v[220:223], v[172:175], v[24:27]
	v_mfma_f32_16x16x32_bf16 v[20:23], v[184:187], v[176:179], v[20:23]
	v_mfma_f32_16x16x32_bf16 v[20:23], v[188:191], v[180:183], v[20:23]
	v_mfma_f32_16x16x32_bf16 v[16:19], v[192:195], v[176:179], v[16:19]
	v_mfma_f32_16x16x32_bf16 v[16:19], v[196:199], v[180:183], v[16:19]
	v_mfma_f32_16x16x32_bf16 v[12:15], v[208:211], v[176:179], v[12:15]
	v_mfma_f32_16x16x32_bf16 v[12:15], v[212:215], v[180:183], v[12:15]
	v_mfma_f32_16x16x32_bf16 v[8:11], v[216:219], v[176:179], v[8:11]
	v_mfma_f32_16x16x32_bf16 v[8:11], v[220:223], v[180:183], v[8:11]
	s_setprio 0
	s_barrier
	s_add_i32 s50, s50, 2
	s_add_u32 s44, s44, 0x100
	s_addc_u32 s45, s45, 0
	s_add_u32 s33, s33, 0x100
	s_addc_u32 s43, s43, 0
	s_cmp_gt_u32 s50, 29
	s_cbranch_scc0 .LBB0_986
	s_and_b64 vcc, exec, s[10:11]
	s_cbranch_vccz .LBB0_1031
	s_barrier
	s_cmp_gt_i32 s35, 15
	s_mov_b64 s[12:13], -1
	s_cbranch_scc1 .LBB0_1032

.LBB0_1482:
	s_add_i32 s26, s12, 2
	s_cmp_eq_u32 s57, s12
	s_cselect_b32 s13, s43, s51
	s_cselect_b32 s12, s42, s50
	s_cselect_b32 s65, s45, s15
	s_cselect_b32 s64, s44, s14
	s_add_i32 s27, 0, 0x10000
	s_movk_i32 s66, 0xff80
	v_add_u32_e32 v121, s27, v7
	s_add_i32 s63, 0, 0x14000
	v_lshl_add_u64 v[178:179], s[50:51], 0, v[108:109]
	s_mov_b32 s67, -1
	ds_read_b128 v[110:113], v119
	ds_read_b128 v[114:117], v119 offset:1024
	ds_read_b128 v[122:125], v119 offset:2048
	ds_read_b128 v[126:129], v119 offset:3072
	ds_read_b128 v[130:133], v119 offset:4096
	ds_read_b128 v[134:137], v119 offset:5120
	ds_read_b128 v[138:141], v119 offset:6144
	ds_read_b128 v[142:145], v119 offset:7168
	ds_read_b128 v[146:149], v121
	ds_read_b128 v[150:153], v121 offset:1024
	ds_read_b128 v[154:157], v121 offset:2048
	ds_read_b128 v[158:161], v121 offset:3072
	v_add_u32_e32 v121, s63, v7
	v_lshl_add_u64 v[178:179], v[178:179], 0, s[66:67]
	s_add_i32 m0, s39, 0xc000
	ds_read_b128 v[162:165], v121
	ds_read_b128 v[166:169], v121 offset:1024
	ds_read_b128 v[170:173], v121 offset:2048
	ds_read_b128 v[174:177], v121 offset:3072
	global_load_lds_dwordx4 v[178:179], off
	s_waitcnt vmcnt(7)
	s_waitcnt lgkmcnt(0)
	s_barrier
	s_setprio 1
	s_waitcnt lgkmcnt(0)
	v_mfma_f32_16x16x32_bf16 v[100:103], v[146:149], v[110:113], v[100:103]
	v_mfma_f32_16x16x32_bf16 v[100:103], v[150:153], v[114:117], v[100:103]
	v_mfma_f32_16x16x32_bf16 v[96:99], v[154:157], v[110:113], v[96:99]
	v_mfma_f32_16x16x32_bf16 v[96:99], v[158:161], v[114:117], v[96:99]
	v_mfma_f32_16x16x32_bf16 v[88:91], v[162:165], v[110:113], v[88:91]
	v_mfma_f32_16x16x32_bf16 v[88:91], v[166:169], v[114:117], v[88:91]
	v_mfma_f32_16x16x32_bf16 v[84:87], v[170:173], v[110:113], v[84:87]
	v_mfma_f32_16x16x32_bf16 v[84:87], v[174:177], v[114:117], v[84:87]
	v_mfma_f32_16x16x32_bf16 v[92:95], v[146:149], v[122:125], v[92:95]
	v_mfma_f32_16x16x32_bf16 v[92:95], v[150:153], v[126:129], v[92:95]
	v_mfma_f32_16x16x32_bf16 v[80:83], v[154:157], v[122:125], v[80:83]
	v_mfma_f32_16x16x32_bf16 v[80:83], v[158:161], v[126:129], v[80:83]
	v_mfma_f32_16x16x32_bf16 v[76:79], v[162:165], v[122:125], v[76:79]
	v_mfma_f32_16x16x32_bf16 v[76:79], v[166:169], v[126:129], v[76:79]
	v_mfma_f32_16x16x32_bf16 v[68:71], v[170:173], v[122:125], v[68:71]
	v_mfma_f32_16x16x32_bf16 v[68:71], v[174:177], v[126:129], v[68:71]
	v_mfma_f32_16x16x32_bf16 v[72:75], v[146:149], v[130:133], v[72:75]
	v_mfma_f32_16x16x32_bf16 v[72:75], v[150:153], v[134:137], v[72:75]
	v_mfma_f32_16x16x32_bf16 v[64:67], v[154:157], v[130:133], v[64:67]
	v_mfma_f32_16x16x32_bf16 v[64:67], v[158:161], v[134:137], v[64:67]
	v_mfma_f32_16x16x32_bf16 v[60:63], v[162:165], v[130:133], v[60:63]
	v_mfma_f32_16x16x32_bf16 v[60:63], v[166:169], v[134:137], v[60:63]
	v_mfma_f32_16x16x32_bf16 v[52:55], v[170:173], v[130:133], v[52:55]
	v_mfma_f32_16x16x32_bf16 v[52:55], v[174:177], v[134:137], v[52:55]
	v_mfma_f32_16x16x32_bf16 v[56:59], v[146:149], v[138:141], v[56:59]
	v_mfma_f32_16x16x32_bf16 v[56:59], v[150:153], v[142:145], v[56:59]
	v_mfma_f32_16x16x32_bf16 v[48:51], v[154:157], v[138:141], v[48:51]
	v_mfma_f32_16x16x32_bf16 v[48:51], v[158:161], v[142:145], v[48:51]
	v_mfma_f32_16x16x32_bf16 v[44:47], v[162:165], v[138:141], v[44:47]
	v_mfma_f32_16x16x32_bf16 v[44:47], v[166:169], v[142:145], v[44:47]
	v_mfma_f32_16x16x32_bf16 v[40:43], v[170:173], v[138:141], v[40:43]
	v_mfma_f32_16x16x32_bf16 v[40:43], v[174:177], v[142:145], v[40:43]
	s_setprio 0
	s_barrier
	s_add_i32 s27, s27, s22
	v_lshl_add_u64 v[178:179], s[64:65], 0, v[2:3]
	s_mov_b32 m0, s27
	ds_read_b128 v[110:113], v120 offset:16384
	ds_read_b128 v[114:117], v120 offset:17408
	ds_read_b128 v[122:125], v120 offset:18432
	ds_read_b128 v[126:129], v120 offset:19456
	global_load_lds_dwordx4 v[178:179], off
	s_add_i32 m0, s27, 0x2000
	v_lshl_add_u64 v[180:181], s[64:65], 0, v[4:5]
	s_add_u32 s64, s64, s90
	s_addc_u32 s65, s65, 0
	s_add_i32 s27, s63, s22
	global_load_lds_dwordx4 v[180:181], off
	v_lshl_add_u64 v[182:183], s[64:65], 0, v[2:3]
	s_mov_b32 m0, s27
	v_lshl_add_u64 v[184:185], s[64:65], 0, v[4:5]
	global_load_lds_dwordx4 v[182:183], off
	s_add_i32 m0, s27, 0x2000
	v_lshl_add_u64 v[186:187], s[12:13], 0, v[106:107]
	global_load_lds_dwordx4 v[184:185], off
	s_mov_b32 m0, s39
	v_lshl_add_u64 v[188:189], s[12:13], 0, v[104:105]
	global_load_lds_dwordx4 v[186:187], off
	s_mov_b32 m0, s40
	s_nop 0
	global_load_lds_dwordx4 v[188:189], off
	s_waitcnt vmcnt(7)
	s_waitcnt lgkmcnt(0)
	s_barrier
	s_setprio 1
	s_waitcnt lgkmcnt(0)
	v_mfma_f32_16x16x32_bf16 v[36:39], v[146:149], v[110:113], v[36:39]
	v_mfma_f32_16x16x32_bf16 v[36:39], v[150:153], v[114:117], v[36:39]
	v_mfma_f32_16x16x32_bf16 v[32:35], v[154:157], v[110:113], v[32:35]
	v_mfma_f32_16x16x32_bf16 v[32:35], v[158:161], v[114:117], v[32:35]
	v_mfma_f32_16x16x32_bf16 v[28:31], v[162:165], v[110:113], v[28:31]
	v_mfma_f32_16x16x32_bf16 v[28:31], v[166:169], v[114:117], v[28:31]
	v_mfma_f32_16x16x32_bf16 v[24:27], v[170:173], v[110:113], v[24:27]
	v_mfma_f32_16x16x32_bf16 v[24:27], v[174:177], v[114:117], v[24:27]
	v_mfma_f32_16x16x32_bf16 v[20:23], v[146:149], v[122:125], v[20:23]
	v_mfma_f32_16x16x32_bf16 v[20:23], v[150:153], v[126:129], v[20:23]
	v_mfma_f32_16x16x32_bf16 v[16:19], v[154:157], v[122:125], v[16:19]
	v_mfma_f32_16x16x32_bf16 v[16:19], v[158:161], v[126:129], v[16:19]
	v_mfma_f32_16x16x32_bf16 v[12:15], v[162:165], v[122:125], v[12:15]
	v_mfma_f32_16x16x32_bf16 v[12:15], v[166:169], v[126:129], v[12:15]
	v_mfma_f32_16x16x32_bf16 v[8:11], v[170:173], v[122:125], v[8:11]
	v_mfma_f32_16x16x32_bf16 v[8:11], v[174:177], v[126:129], v[8:11]
	s_setprio 0
	s_barrier
	s_add_i32 s27, 0, 0x18000
	s_add_i32 s63, 0, 0x1c000
	s_add_u32 s12, s12, s90
	v_add_u32_e32 v121, s27, v7
	s_addc_u32 s13, s13, 0
	ds_read_b128 v[110:113], v119 offset:32768
	ds_read_b128 v[114:117], v119 offset:33792
	ds_read_b128 v[122:125], v119 offset:34816
	ds_read_b128 v[126:129], v119 offset:35840
	ds_read_b128 v[130:133], v119 offset:36864
	ds_read_b128 v[134:137], v119 offset:37888
	ds_read_b128 v[138:141], v119 offset:38912
	ds_read_b128 v[142:145], v119 offset:39936
	ds_read_b128 v[146:149], v121
	ds_read_b128 v[150:153], v121 offset:1024
	ds_read_b128 v[154:157], v121 offset:2048
	ds_read_b128 v[158:161], v121 offset:3072
	v_add_u32_e32 v121, s63, v7
	v_lshl_add_u64 v[190:191], s[12:13], 0, v[106:107]
	s_mov_b32 m0, s41
	ds_read_b128 v[162:165], v121
	ds_read_b128 v[166:169], v121 offset:1024
	ds_read_b128 v[170:173], v121 offset:2048
	ds_read_b128 v[174:177], v121 offset:3072
	global_load_lds_dwordx4 v[190:191], off
	s_waitcnt vmcnt(7)
	s_waitcnt lgkmcnt(0)
	s_barrier
	s_setprio 1
	s_waitcnt lgkmcnt(0)
	v_mfma_f32_16x16x32_bf16 v[100:103], v[146:149], v[110:113], v[100:103]
	v_mfma_f32_16x16x32_bf16 v[100:103], v[150:153], v[114:117], v[100:103]
	v_mfma_f32_16x16x32_bf16 v[96:99], v[154:157], v[110:113], v[96:99]
	v_mfma_f32_16x16x32_bf16 v[96:99], v[158:161], v[114:117], v[96:99]
	v_mfma_f32_16x16x32_bf16 v[88:91], v[162:165], v[110:113], v[88:91]
	v_mfma_f32_16x16x32_bf16 v[88:91], v[166:169], v[114:117], v[88:91]
	v_mfma_f32_16x16x32_bf16 v[84:87], v[170:173], v[110:113], v[84:87]
	v_mfma_f32_16x16x32_bf16 v[84:87], v[174:177], v[114:117], v[84:87]
	v_mfma_f32_16x16x32_bf16 v[92:95], v[146:149], v[122:125], v[92:95]
	v_mfma_f32_16x16x32_bf16 v[92:95], v[150:153], v[126:129], v[92:95]
	v_mfma_f32_16x16x32_bf16 v[80:83], v[154:157], v[122:125], v[80:83]
	v_mfma_f32_16x16x32_bf16 v[80:83], v[158:161], v[126:129], v[80:83]
	v_mfma_f32_16x16x32_bf16 v[76:79], v[162:165], v[122:125], v[76:79]
	v_mfma_f32_16x16x32_bf16 v[76:79], v[166:169], v[126:129], v[76:79]
	v_mfma_f32_16x16x32_bf16 v[68:71], v[170:173], v[122:125], v[68:71]
	v_mfma_f32_16x16x32_bf16 v[68:71], v[174:177], v[126:129], v[68:71]
	v_mfma_f32_16x16x32_bf16 v[72:75], v[146:149], v[130:133], v[72:75]
	v_mfma_f32_16x16x32_bf16 v[72:75], v[150:153], v[134:137], v[72:75]
	v_mfma_f32_16x16x32_bf16 v[64:67], v[154:157], v[130:133], v[64:67]
	v_mfma_f32_16x16x32_bf16 v[64:67], v[158:161], v[134:137], v[64:67]
	v_mfma_f32_16x16x32_bf16 v[60:63], v[162:165], v[130:133], v[60:63]
	v_mfma_f32_16x16x32_bf16 v[60:63], v[166:169], v[134:137], v[60:63]
	v_mfma_f32_16x16x32_bf16 v[52:55], v[170:173], v[130:133], v[52:55]
	v_mfma_f32_16x16x32_bf16 v[52:55], v[174:177], v[134:137], v[52:55]
	v_mfma_f32_16x16x32_bf16 v[56:59], v[146:149], v[138:141], v[56:59]
	v_mfma_f32_16x16x32_bf16 v[56:59], v[150:153], v[142:145], v[56:59]
	v_mfma_f32_16x16x32_bf16 v[48:51], v[154:157], v[138:141], v[48:51]
	v_mfma_f32_16x16x32_bf16 v[48:51], v[158:161], v[142:145], v[48:51]
	v_mfma_f32_16x16x32_bf16 v[44:47], v[162:165], v[138:141], v[44:47]
	v_mfma_f32_16x16x32_bf16 v[44:47], v[166:169], v[142:145], v[44:47]
	v_mfma_f32_16x16x32_bf16 v[40:43], v[170:173], v[138:141], v[40:43]
	v_mfma_f32_16x16x32_bf16 v[40:43], v[174:177], v[142:145], v[40:43]
	s_setprio 0
	s_barrier
	s_add_i32 s12, s27, s22
	v_lshl_add_u64 v[130:131], v[178:179], 0, s[0:1]
	s_mov_b32 m0, s12
	ds_read_b128 v[110:113], v120 offset:49152
	ds_read_b128 v[114:117], v120 offset:50176
	ds_read_b128 v[122:125], v120 offset:51200
	ds_read_b128 v[126:129], v120 offset:52224
	global_load_lds_dwordx4 v[130:131], off
	v_lshl_add_u64 v[130:131], v[180:181], 0, s[0:1]
	s_add_i32 m0, s12, 0x2000
	s_add_i32 s12, s63, s22
	global_load_lds_dwordx4 v[130:131], off
	v_lshl_add_u64 v[130:131], v[182:183], 0, s[0:1]
	s_mov_b32 m0, s12
	s_nop 0
	global_load_lds_dwordx4 v[130:131], off
	v_lshl_add_u64 v[130:131], v[184:185], 0, s[0:1]
	s_add_i32 m0, s12, 0x2000
	s_nop 0
	global_load_lds_dwordx4 v[130:131], off
	v_lshl_add_u64 v[130:131], v[186:187], 0, s[0:1]
	s_mov_b32 m0, s53
	s_nop 0
	global_load_lds_dwordx4 v[130:131], off
	v_lshl_add_u64 v[130:131], v[188:189], 0, s[0:1]
	s_mov_b32 m0, s54
	s_nop 0
	global_load_lds_dwordx4 v[130:131], off
	s_waitcnt vmcnt(7)
	s_waitcnt lgkmcnt(0)
	s_barrier
	s_setprio 1
	s_waitcnt lgkmcnt(0)
	v_mfma_f32_16x16x32_bf16 v[36:39], v[146:149], v[110:113], v[36:39]
	v_mfma_f32_16x16x32_bf16 v[36:39], v[150:153], v[114:117], v[36:39]
	v_mfma_f32_16x16x32_bf16 v[32:35], v[154:157], v[110:113], v[32:35]
	v_mfma_f32_16x16x32_bf16 v[32:35], v[158:161], v[114:117], v[32:35]
	v_mfma_f32_16x16x32_bf16 v[28:31], v[162:165], v[110:113], v[28:31]
	v_mfma_f32_16x16x32_bf16 v[28:31], v[166:169], v[114:117], v[28:31]
	v_mfma_f32_16x16x32_bf16 v[24:27], v[170:173], v[110:113], v[24:27]
	v_mfma_f32_16x16x32_bf16 v[24:27], v[174:177], v[114:117], v[24:27]
	v_mfma_f32_16x16x32_bf16 v[20:23], v[146:149], v[122:125], v[20:23]
	v_mfma_f32_16x16x32_bf16 v[20:23], v[150:153], v[126:129], v[20:23]
	v_mfma_f32_16x16x32_bf16 v[16:19], v[154:157], v[122:125], v[16:19]
	v_mfma_f32_16x16x32_bf16 v[16:19], v[158:161], v[126:129], v[16:19]
	v_mfma_f32_16x16x32_bf16 v[12:15], v[162:165], v[122:125], v[12:15]
	v_mfma_f32_16x16x32_bf16 v[12:15], v[166:169], v[126:129], v[12:15]
	v_mfma_f32_16x16x32_bf16 v[8:11], v[170:173], v[122:125], v[8:11]
	v_mfma_f32_16x16x32_bf16 v[8:11], v[174:177], v[126:129], v[8:11]
	s_setprio 0
	s_barrier
	s_add_u32 s50, s50, 0x100
	s_addc_u32 s51, s51, 0
	s_add_u32 s14, s14, 0x100
	s_addc_u32 s15, s15, 0
	s_cmp_ge_u32 s26, s55
	s_mov_b32 s12, s26
	s_cbranch_scc0 .LBB0_1482
	s_and_b64 vcc, exec, s[36:37]
	s_cbranch_vccz .LBB0_1485
	s_barrier
